# prep-phase stores (bf16 weights, modulation vectors) written through (sc1) as well
# baseline (speedup 1.0000x reference)
.LBB0_155:
	v_lshl_add_u64 v[18:19], v[60:61], 0, s[20:21]
	v_add_co_u32_e64 v20, s[0:1], s29, v18
	s_nop 1
	v_addc_co_u32_e64 v21, s[0:1], 0, v19, s[0:1]
	v_add_co_u32_e64 v26, s[0:1], s5, v18
	s_add_u32 s20, s20, 0x30000
	s_nop 1
	v_addc_co_u32_e64 v27, s[0:1], 0, v19, s[0:1]
	s_mov_b32 s0, 0x9000
	v_add_co_u32_e64 v46, s[0:1], s0, v18
	s_nop 1
	global_load_dword v108, v[18:19], off
	s_nop 1
	global_load_dword v109, v[20:21], off
	s_nop 1
	global_load_dword v110, v[26:27], off
	s_nop 1
	v_addc_co_u32_e64 v47, s[0:1], 0, v19, s[0:1]
	v_add_co_u32_e64 v48, s[0:1], s50, v18
	s_nop 1
	v_addc_co_u32_e64 v49, s[0:1], 0, v19, s[0:1]
	s_mov_b32 s0, 0xf000
	v_add_co_u32_e64 v76, s[0:1], s0, v18
	s_addc_u32 s21, s21, 0
	s_nop 1
	v_addc_co_u32_e64 v77, s[0:1], 0, v19, s[0:1]
	s_mov_b32 s0, 0x12000
	v_add_co_u32_e64 v78, s[0:1], s0, v18
	s_nop 1
	v_addc_co_u32_e64 v79, s[0:1], 0, v19, s[0:1]
	s_nop 1
	global_load_dword v111, v[46:47], off
	s_nop 1
	global_load_dword v112, v[48:49], off
	s_nop 1
	global_load_dword v113, v[76:77], off
	s_nop 1
	global_load_dword v114, v[78:79], off
	s_mov_b32 s0, 0x15000
	v_add_co_u32_e64 v80, s[0:1], s0, v18
	s_nop 1
	v_addc_co_u32_e64 v81, s[0:1], 0, v19, s[0:1]
	v_add_co_u32_e64 v30, s[0:1], s96, v18
	s_nop 1
	global_load_dword v115, v[80:81], off
	s_nop 1
	v_addc_co_u32_e64 v31, s[0:1], 0, v19, s[0:1]
	s_mov_b32 s0, 0x1b000
	v_add_co_u32_e64 v34, s[0:1], s0, v18
	s_nop 1
	v_addc_co_u32_e64 v35, s[0:1], 0, v19, s[0:1]
	s_mov_b32 s0, 0x1e000
	v_add_co_u32_e64 v40, s[0:1], s0, v18
	s_nop 1
	v_addc_co_u32_e64 v41, s[0:1], 0, v19, s[0:1]
	s_mov_b32 s0, 0x21000
	v_add_co_u32_e64 v32, s[0:1], s0, v18
	s_nop 1
	v_addc_co_u32_e64 v33, s[0:1], 0, v19, s[0:1]
	s_mov_b32 s0, 0x24000
	v_add_co_u32_e64 v38, s[0:1], s0, v18
	s_nop 1
	v_addc_co_u32_e64 v39, s[0:1], 0, v19, s[0:1]
	s_mov_b32 s0, 0x27000
	v_add_co_u32_e64 v42, s[0:1], s0, v18
	s_nop 1
	v_addc_co_u32_e64 v43, s[0:1], 0, v19, s[0:1]
	s_mov_b32 s0, 0x2a000
	v_add_co_u32_e64 v44, s[0:1], s0, v18
	s_nop 1
	v_addc_co_u32_e64 v45, s[0:1], 0, v19, s[0:1]
	s_mov_b32 s0, 0x2d000
	v_add_co_u32_e64 v36, s[0:1], s0, v18
	s_nop 1
	v_addc_co_u32_e64 v37, s[0:1], 0, v19, s[0:1]
	s_nop 1
	global_load_dword v116, v[30:31], off
	s_nop 1
	global_load_dword v117, v[34:35], off
	s_nop 1
	global_load_dword v118, v[40:41], off
	s_nop 1
	global_load_dword v119, v[32:33], off
	s_nop 1
	global_load_dword v120, v[38:39], off
	s_nop 1
	global_load_dword v121, v[42:43], off
	s_nop 1
	global_load_dword v122, v[44:45], off
	s_nop 1
	global_load_dword v123, v[36:37], off
	v_lshl_add_u64 v[18:19], v[60:61], 0, s[20:21]
	v_add_co_u32_e64 v20, s[0:1], s29, v18
	s_nop 1
	v_addc_co_u32_e64 v21, s[0:1], 0, v19, s[0:1]
	v_add_co_u32_e64 v26, s[0:1], s5, v18
	s_add_u32 s20, s20, 0x30000
	s_nop 1
	v_addc_co_u32_e64 v27, s[0:1], 0, v19, s[0:1]
	s_mov_b32 s0, 0x9000
	v_add_co_u32_e64 v46, s[0:1], s0, v18
	s_nop 1
	global_load_dword v124, v[18:19], off
	s_nop 1
	global_load_dword v125, v[20:21], off
	s_nop 1
	global_load_dword v126, v[26:27], off
	s_nop 1
	v_addc_co_u32_e64 v47, s[0:1], 0, v19, s[0:1]
	v_add_co_u32_e64 v48, s[0:1], s50, v18
	s_nop 1
	v_addc_co_u32_e64 v49, s[0:1], 0, v19, s[0:1]
	s_mov_b32 s0, 0xf000
	v_add_co_u32_e64 v76, s[0:1], s0, v18
	s_addc_u32 s21, s21, 0
	s_nop 1
	v_addc_co_u32_e64 v77, s[0:1], 0, v19, s[0:1]
	s_mov_b32 s0, 0x12000
	v_add_co_u32_e64 v78, s[0:1], s0, v18
	s_nop 1
	v_addc_co_u32_e64 v79, s[0:1], 0, v19, s[0:1]
	s_nop 1
	global_load_dword v127, v[46:47], off
	s_nop 1
	global_load_dword v128, v[48:49], off
	s_nop 1
	global_load_dword v129, v[76:77], off
	s_nop 1
	global_load_dword v130, v[78:79], off
	s_mov_b32 s0, 0x15000
	v_add_co_u32_e64 v80, s[0:1], s0, v18
	s_nop 1
	v_addc_co_u32_e64 v81, s[0:1], 0, v19, s[0:1]
	v_add_co_u32_e64 v30, s[0:1], s96, v18
	s_nop 1
	global_load_dword v131, v[80:81], off
	s_nop 1
	v_addc_co_u32_e64 v31, s[0:1], 0, v19, s[0:1]
	s_mov_b32 s0, 0x1b000
	v_add_co_u32_e64 v34, s[0:1], s0, v18
	s_nop 1
	v_addc_co_u32_e64 v35, s[0:1], 0, v19, s[0:1]
	s_mov_b32 s0, 0x1e000
	v_add_co_u32_e64 v40, s[0:1], s0, v18
	s_nop 1
	v_addc_co_u32_e64 v41, s[0:1], 0, v19, s[0:1]
	s_mov_b32 s0, 0x21000
	v_add_co_u32_e64 v32, s[0:1], s0, v18
	s_nop 1
	v_addc_co_u32_e64 v33, s[0:1], 0, v19, s[0:1]
	s_mov_b32 s0, 0x24000
	v_add_co_u32_e64 v38, s[0:1], s0, v18
	s_nop 1
	v_addc_co_u32_e64 v39, s[0:1], 0, v19, s[0:1]
	s_mov_b32 s0, 0x27000
	v_add_co_u32_e64 v42, s[0:1], s0, v18
	s_nop 1
	v_addc_co_u32_e64 v43, s[0:1], 0, v19, s[0:1]
	s_mov_b32 s0, 0x2a000
	v_add_co_u32_e64 v44, s[0:1], s0, v18
	s_nop 1
	v_addc_co_u32_e64 v45, s[0:1], 0, v19, s[0:1]
	s_mov_b32 s0, 0x2d000
	v_add_co_u32_e64 v36, s[0:1], s0, v18
	s_nop 1
	v_addc_co_u32_e64 v37, s[0:1], 0, v19, s[0:1]
	s_nop 1
	global_load_dword v132, v[30:31], off
	s_nop 1
	global_load_dword v133, v[34:35], off
	s_nop 1
	global_load_dword v134, v[40:41], off
	s_nop 1
	global_load_dword v135, v[32:33], off
	s_nop 1
	global_load_dword v136, v[38:39], off
	s_nop 1
	global_load_dword v137, v[42:43], off
	s_nop 1
	global_load_dword v138, v[44:45], off
	s_nop 1
	global_load_dword v139, v[36:37], off
	v_lshl_add_u64 v[18:19], v[60:61], 0, s[20:21]
	v_add_co_u32_e64 v20, s[0:1], s29, v18
	s_nop 1
	v_addc_co_u32_e64 v21, s[0:1], 0, v19, s[0:1]
	v_add_co_u32_e64 v26, s[0:1], s5, v18
	s_add_u32 s20, s20, 0x30000
	s_nop 1
	v_addc_co_u32_e64 v27, s[0:1], 0, v19, s[0:1]
	s_mov_b32 s0, 0x9000
	v_add_co_u32_e64 v46, s[0:1], s0, v18
	s_nop 1
	global_load_dword v140, v[18:19], off
	s_nop 1
	global_load_dword v141, v[20:21], off
	s_nop 1
	global_load_dword v142, v[26:27], off
	s_nop 1
	v_addc_co_u32_e64 v47, s[0:1], 0, v19, s[0:1]
	v_add_co_u32_e64 v48, s[0:1], s50, v18
	s_nop 1
	v_addc_co_u32_e64 v49, s[0:1], 0, v19, s[0:1]
	s_mov_b32 s0, 0xf000
	v_add_co_u32_e64 v76, s[0:1], s0, v18
	s_addc_u32 s21, s21, 0
	s_nop 1
	v_addc_co_u32_e64 v77, s[0:1], 0, v19, s[0:1]
	s_mov_b32 s0, 0x12000
	v_add_co_u32_e64 v78, s[0:1], s0, v18
	s_nop 1
	v_addc_co_u32_e64 v79, s[0:1], 0, v19, s[0:1]
	s_nop 1
	global_load_dword v143, v[46:47], off
	s_nop 1
	global_load_dword v144, v[48:49], off
	s_nop 1
	global_load_dword v145, v[76:77], off
	s_nop 1
	global_load_dword v146, v[78:79], off
	s_mov_b32 s0, 0x15000
	v_add_co_u32_e64 v80, s[0:1], s0, v18
	s_nop 1
	v_addc_co_u32_e64 v81, s[0:1], 0, v19, s[0:1]
	v_add_co_u32_e64 v30, s[0:1], s96, v18
	s_nop 1
	global_load_dword v147, v[80:81], off
	s_nop 1
	v_addc_co_u32_e64 v31, s[0:1], 0, v19, s[0:1]
	s_mov_b32 s0, 0x1b000
	v_add_co_u32_e64 v34, s[0:1], s0, v18
	s_nop 1
	v_addc_co_u32_e64 v35, s[0:1], 0, v19, s[0:1]
	s_mov_b32 s0, 0x1e000
	v_add_co_u32_e64 v40, s[0:1], s0, v18
	s_nop 1
	v_addc_co_u32_e64 v41, s[0:1], 0, v19, s[0:1]
	s_mov_b32 s0, 0x21000
	v_add_co_u32_e64 v32, s[0:1], s0, v18
	s_nop 1
	v_addc_co_u32_e64 v33, s[0:1], 0, v19, s[0:1]
	s_mov_b32 s0, 0x24000
	v_add_co_u32_e64 v38, s[0:1], s0, v18
	s_nop 1
	v_addc_co_u32_e64 v39, s[0:1], 0, v19, s[0:1]
	s_mov_b32 s0, 0x27000
	v_add_co_u32_e64 v42, s[0:1], s0, v18
	s_nop 1
	v_addc_co_u32_e64 v43, s[0:1], 0, v19, s[0:1]
	s_mov_b32 s0, 0x2a000
	v_add_co_u32_e64 v44, s[0:1], s0, v18
	s_nop 1
	v_addc_co_u32_e64 v45, s[0:1], 0, v19, s[0:1]
	s_mov_b32 s0, 0x2d000
	v_add_co_u32_e64 v36, s[0:1], s0, v18
	s_nop 1
	v_addc_co_u32_e64 v37, s[0:1], 0, v19, s[0:1]
	s_nop 1
	global_load_dword v148, v[30:31], off
	s_nop 1
	global_load_dword v149, v[34:35], off
	s_nop 1
	global_load_dword v150, v[40:41], off
	s_nop 1
	global_load_dword v151, v[32:33], off
	s_nop 1
	global_load_dword v152, v[38:39], off
	s_nop 1
	global_load_dword v153, v[42:43], off
	s_nop 1
	global_load_dword v154, v[44:45], off
	s_nop 1
	global_load_dword v155, v[36:37], off
	v_lshl_add_u64 v[18:19], v[60:61], 0, s[20:21]
	v_add_co_u32_e64 v20, s[0:1], s29, v18
	s_nop 1
	v_addc_co_u32_e64 v21, s[0:1], 0, v19, s[0:1]
	v_add_co_u32_e64 v26, s[0:1], s5, v18
	s_add_u32 s20, s20, 0x30000
	s_nop 1
	v_addc_co_u32_e64 v27, s[0:1], 0, v19, s[0:1]
	s_mov_b32 s0, 0x9000
	v_add_co_u32_e64 v46, s[0:1], s0, v18
	s_nop 1
	global_load_dword v156, v[18:19], off
	s_nop 1
	global_load_dword v157, v[20:21], off
	s_nop 1
	global_load_dword v158, v[26:27], off
	s_nop 1
	v_addc_co_u32_e64 v47, s[0:1], 0, v19, s[0:1]
	v_add_co_u32_e64 v48, s[0:1], s50, v18
	s_nop 1
	v_addc_co_u32_e64 v49, s[0:1], 0, v19, s[0:1]
	s_mov_b32 s0, 0xf000
	v_add_co_u32_e64 v76, s[0:1], s0, v18
	s_addc_u32 s21, s21, 0
	s_nop 1
	v_addc_co_u32_e64 v77, s[0:1], 0, v19, s[0:1]
	s_mov_b32 s0, 0x12000
	v_add_co_u32_e64 v78, s[0:1], s0, v18
	s_nop 1
	v_addc_co_u32_e64 v79, s[0:1], 0, v19, s[0:1]
	s_nop 1
	global_load_dword v159, v[46:47], off
	s_nop 1
	global_load_dword v160, v[48:49], off
	s_nop 1
	global_load_dword v161, v[76:77], off
	s_nop 1
	global_load_dword v162, v[78:79], off
	s_mov_b32 s0, 0x15000
	v_add_co_u32_e64 v80, s[0:1], s0, v18
	s_nop 1
	v_addc_co_u32_e64 v81, s[0:1], 0, v19, s[0:1]
	v_add_co_u32_e64 v30, s[0:1], s96, v18
	s_nop 1
	global_load_dword v163, v[80:81], off
	s_nop 1
	v_addc_co_u32_e64 v31, s[0:1], 0, v19, s[0:1]
	s_mov_b32 s0, 0x1b000
	v_add_co_u32_e64 v34, s[0:1], s0, v18
	s_nop 1
	v_addc_co_u32_e64 v35, s[0:1], 0, v19, s[0:1]
	s_mov_b32 s0, 0x1e000
	v_add_co_u32_e64 v40, s[0:1], s0, v18
	s_nop 1
	v_addc_co_u32_e64 v41, s[0:1], 0, v19, s[0:1]
	s_mov_b32 s0, 0x21000
	v_add_co_u32_e64 v32, s[0:1], s0, v18
	s_nop 1
	v_addc_co_u32_e64 v33, s[0:1], 0, v19, s[0:1]
	s_mov_b32 s0, 0x24000
	v_add_co_u32_e64 v38, s[0:1], s0, v18
	s_nop 1
	v_addc_co_u32_e64 v39, s[0:1], 0, v19, s[0:1]
	s_mov_b32 s0, 0x27000
	v_add_co_u32_e64 v42, s[0:1], s0, v18
	s_nop 1
	v_addc_co_u32_e64 v43, s[0:1], 0, v19, s[0:1]
	s_mov_b32 s0, 0x2a000
	v_add_co_u32_e64 v44, s[0:1], s0, v18
	s_nop 1
	v_addc_co_u32_e64 v45, s[0:1], 0, v19, s[0:1]
	s_mov_b32 s0, 0x2d000
	v_add_co_u32_e64 v36, s[0:1], s0, v18
	s_nop 1
	v_addc_co_u32_e64 v37, s[0:1], 0, v19, s[0:1]
	s_nop 1
	global_load_dword v164, v[30:31], off
	s_nop 1
	global_load_dword v165, v[34:35], off
	s_nop 1
	global_load_dword v166, v[40:41], off
	s_nop 1
	global_load_dword v167, v[32:33], off
	s_nop 1
	global_load_dword v168, v[38:39], off
	s_nop 1
	global_load_dword v169, v[42:43], off
	s_nop 1
	global_load_dword v170, v[44:45], off
	s_nop 1
	global_load_dword v171, v[36:37], off
	s_mov_b64 s[20:21], 0
	s_waitcnt vmcnt(0)
	v_lshl_add_u64 v[18:19], v[60:61], 0, s[20:21]
	v_add_co_u32_e64 v20, s[0:1], s29, v18
	ds_read_b128 v[72:75], v64
	ds_read_b128 v[6:9], v64 offset:16
	ds_read_b128 v[22:25], v64 offset:4096
	ds_read_b128 v[14:17], v64 offset:8192
	ds_read_b128 v[10:13], v64 offset:12288
	ds_read_b128 v[2:5], v64 offset:16384
	v_addc_co_u32_e64 v21, s[0:1], 0, v19, s[0:1]
	v_add_co_u32_e64 v26, s[0:1], s5, v18
	s_add_u32 s20, s20, 0x30000
	s_nop 0
	v_addc_co_u32_e64 v27, s[0:1], 0, v19, s[0:1]
	s_mov_b32 s0, 0x9000
	s_nop 0
	v_add_co_u32_e64 v46, s[0:1], s0, v18
	v_mov_b32_e32 v50, v108
	v_mov_b32_e32 v51, v109
	v_mov_b32_e32 v52, v110
	v_addc_co_u32_e64 v47, s[0:1], 0, v19, s[0:1]
	v_add_co_u32_e64 v48, s[0:1], s50, v18
	ds_read_b128 v[26:29], v64 offset:20480
	s_nop 0
	v_addc_co_u32_e64 v49, s[0:1], 0, v19, s[0:1]
	s_mov_b32 s0, 0xf000
	s_nop 0
	v_add_co_u32_e64 v76, s[0:1], s0, v18
	s_addc_u32 s21, s21, 0
	s_nop 0
	v_addc_co_u32_e64 v77, s[0:1], 0, v19, s[0:1]
	s_mov_b32 s0, 0x12000
	s_nop 0
	v_add_co_u32_e64 v78, s[0:1], s0, v18
	s_cmp_eq_u32 s20, 0xc0000
	s_nop 0
	v_addc_co_u32_e64 v79, s[0:1], 0, v19, s[0:1]
	v_mov_b32_e32 v53, v111
	s_nop 0
	v_mov_b32_e32 v49, v112
	s_nop 0
	v_mov_b32_e32 v48, v113
	v_mov_b32_e32 v47, v114
	s_mov_b32 s0, 0x15000
	v_add_co_u32_e64 v80, s[0:1], s0, v18
	ds_read_b128 v[82:85], v64 offset:12304
	ds_read_b128 v[86:89], v64 offset:16400
	v_addc_co_u32_e64 v81, s[0:1], 0, v19, s[0:1]
	v_add_co_u32_e64 v30, s[0:1], s96, v18
	v_mov_b32_e32 v46, v115
	s_nop 0
	v_addc_co_u32_e64 v31, s[0:1], 0, v19, s[0:1]
	s_mov_b32 s0, 0x1b000
	s_nop 0
	v_add_co_u32_e64 v34, s[0:1], s0, v18
	ds_read_b128 v[78:81], v64 offset:4112
	s_nop 0
	v_addc_co_u32_e64 v35, s[0:1], 0, v19, s[0:1]
	s_mov_b32 s0, 0x1e000
	s_nop 0
	v_add_co_u32_e64 v40, s[0:1], s0, v18
	ds_read_b128 v[90:93], v64 offset:20496
	s_nop 0
	v_addc_co_u32_e64 v41, s[0:1], 0, v19, s[0:1]
	s_mov_b32 s0, 0x21000
	s_nop 0
	v_add_co_u32_e64 v32, s[0:1], s0, v18
	ds_read_b128 v[94:97], v64 offset:24592
	s_nop 0
	v_addc_co_u32_e64 v33, s[0:1], 0, v19, s[0:1]
	s_mov_b32 s0, 0x24000
	s_nop 0
	v_add_co_u32_e64 v38, s[0:1], s0, v18
	s_waitcnt lgkmcnt(9)
	v_fmac_f32_e32 v65, v50, v22
	v_addc_co_u32_e64 v39, s[0:1], 0, v19, s[0:1]
	s_mov_b32 s0, 0x27000
	s_nop 0
	v_add_co_u32_e64 v42, s[0:1], s0, v18
	s_waitcnt lgkmcnt(6)
	v_fmac_f32_e32 v68, v50, v2
	v_addc_co_u32_e64 v43, s[0:1], 0, v19, s[0:1]
	s_mov_b32 s0, 0x2a000
	s_nop 0
	v_add_co_u32_e64 v44, s[0:1], s0, v18
	v_fmac_f32_e32 v65, v51, v23
	v_addc_co_u32_e64 v45, s[0:1], 0, v19, s[0:1]
	s_mov_b32 s0, 0x2d000
	s_nop 0
	v_add_co_u32_e64 v36, s[0:1], s0, v18
	v_fmac_f32_e32 v68, v51, v3
	s_nop 0
	v_addc_co_u32_e64 v37, s[0:1], 0, v19, s[0:1]
	ds_read_b128 v[18:21], v64 offset:24576
	v_fmac_f32_e32 v65, v52, v24
	v_fmac_f32_e32 v68, v52, v4
	v_fmac_f32_e32 v65, v53, v25
	ds_read_b128 v[22:25], v64 offset:8208
	v_fmac_f32_e32 v68, v53, v5
	ds_read_b128 v[2:5], v64 offset:28672
	ds_read_b128 v[98:101], v64 offset:28688
	v_fmac_f32_e32 v0, v50, v72
	v_fmac_f32_e32 v66, v50, v14
	v_fmac_f32_e32 v67, v50, v10
	s_waitcnt lgkmcnt(9)
	v_fmac_f32_e32 v69, v50, v26
	s_waitcnt lgkmcnt(3)
	v_fmac_f32_e32 v70, v50, v18
	s_waitcnt lgkmcnt(1)
	v_fmac_f32_e32 v71, v50, v2
	v_fmac_f32_e32 v0, v51, v73
	v_fmac_f32_e32 v66, v51, v15
	v_fmac_f32_e32 v67, v51, v11
	v_fmac_f32_e32 v69, v51, v27
	v_fmac_f32_e32 v70, v51, v19
	v_fmac_f32_e32 v71, v51, v3
	v_fmac_f32_e32 v0, v52, v74
	v_fmac_f32_e32 v66, v52, v16
	v_fmac_f32_e32 v67, v52, v12
	v_fmac_f32_e32 v69, v52, v28
	v_fmac_f32_e32 v70, v52, v20
	v_fmac_f32_e32 v71, v52, v4
	v_fmac_f32_e32 v0, v53, v75
	v_fmac_f32_e32 v66, v53, v17
	v_fmac_f32_e32 v67, v53, v13
	v_fmac_f32_e32 v69, v53, v29
	v_fmac_f32_e32 v70, v53, v21
	v_fmac_f32_e32 v71, v53, v5
	ds_read_b128 v[50:53], v64 offset:32
	v_mov_b32_e32 v77, v116
	v_mov_b32_e32 v106, v117
	v_mov_b32_e32 v107, v118
	ds_read_b128 v[2:5], v64 offset:48
	v_mov_b32_e32 v76, v119
	v_mov_b32_e32 v75, v120
	v_mov_b32_e32 v74, v121
	v_mov_b32_e32 v72, v122
	v_mov_b32_e32 v73, v123
	ds_read_b128 v[42:45], v64 offset:4128
	ds_read_b128 v[26:29], v64 offset:4144
	v_fmac_f32_e32 v0, v49, v6
	v_fmac_f32_e32 v65, v49, v78
	v_fmac_f32_e32 v66, v49, v22
	v_fmac_f32_e32 v0, v48, v7
	v_fmac_f32_e32 v65, v48, v79
	v_fmac_f32_e32 v66, v48, v23
	v_fmac_f32_e32 v0, v47, v8
	v_fmac_f32_e32 v65, v47, v80
	v_fmac_f32_e32 v66, v47, v24
	ds_read_b128 v[102:105], v64 offset:8224
	ds_read_b128 v[30:33], v64 offset:8240
	v_fmac_f32_e32 v0, v46, v9
	ds_read_b128 v[6:9], v64 offset:12320
	ds_read_b128 v[34:37], v64 offset:12336
	v_fmac_f32_e32 v65, v46, v81
	ds_read_b128 v[10:13], v64 offset:16416
	ds_read_b128 v[38:41], v64 offset:16432
	v_fmac_f32_e32 v66, v46, v25
	ds_read_b128 v[14:17], v64 offset:20512
	ds_read_b128 v[18:21], v64 offset:24608
	ds_read_b128 v[22:25], v64 offset:28704
	v_fmac_f32_e32 v67, v49, v82
	v_fmac_f32_e32 v68, v49, v86
	v_fmac_f32_e32 v69, v49, v90
	v_fmac_f32_e32 v70, v49, v94
	s_waitcnt lgkmcnt(13)
	v_fmac_f32_e32 v71, v49, v98
	v_fmac_f32_e32 v67, v48, v83
	v_fmac_f32_e32 v68, v48, v87
	v_fmac_f32_e32 v69, v48, v91
	v_fmac_f32_e32 v70, v48, v95
	v_fmac_f32_e32 v71, v48, v99
	v_fmac_f32_e32 v67, v47, v84
	v_fmac_f32_e32 v68, v47, v88
	v_fmac_f32_e32 v69, v47, v92
	v_fmac_f32_e32 v70, v47, v96
	v_fmac_f32_e32 v71, v47, v100
	v_fmac_f32_e32 v67, v46, v85
	v_fmac_f32_e32 v68, v46, v89
	v_fmac_f32_e32 v69, v46, v93
	v_fmac_f32_e32 v70, v46, v97
	v_fmac_f32_e32 v71, v46, v101
	ds_read_b128 v[46:49], v64 offset:24624
	s_waitcnt lgkmcnt(13)
	v_fmac_f32_e32 v0, v77, v50
	s_waitcnt lgkmcnt(11)
	v_fmac_f32_e32 v65, v77, v42
	v_fmac_f32_e32 v0, v106, v51
	v_fmac_f32_e32 v65, v106, v43
	v_fmac_f32_e32 v0, v107, v52
	v_fmac_f32_e32 v65, v107, v44
	v_fmac_f32_e32 v0, v76, v53
	v_fmac_f32_e32 v65, v76, v45
	ds_read_b128 v[42:45], v64 offset:20528
	ds_read_b128 v[50:53], v64 offset:28720
	s_waitcnt lgkmcnt(11)
	v_fmac_f32_e32 v66, v77, v102
	s_waitcnt lgkmcnt(9)
	v_fmac_f32_e32 v67, v77, v6
	s_waitcnt lgkmcnt(7)
	v_fmac_f32_e32 v68, v77, v10
	s_waitcnt lgkmcnt(5)
	v_fmac_f32_e32 v69, v77, v14
	s_waitcnt lgkmcnt(4)
	v_fmac_f32_e32 v70, v77, v18
	s_waitcnt lgkmcnt(3)
	v_fmac_f32_e32 v71, v77, v22
	v_fmac_f32_e32 v66, v106, v103
	v_fmac_f32_e32 v67, v106, v7
	v_fmac_f32_e32 v68, v106, v11
	v_fmac_f32_e32 v69, v106, v15
	v_fmac_f32_e32 v70, v106, v19
	v_fmac_f32_e32 v71, v106, v23
	v_fmac_f32_e32 v66, v107, v104
	v_fmac_f32_e32 v67, v107, v8
	v_fmac_f32_e32 v68, v107, v12
	v_fmac_f32_e32 v69, v107, v16
	v_fmac_f32_e32 v70, v107, v20
	v_fmac_f32_e32 v71, v107, v24
	v_fmac_f32_e32 v66, v76, v105
	v_fmac_f32_e32 v67, v76, v9
	v_fmac_f32_e32 v68, v76, v13
	v_fmac_f32_e32 v69, v76, v17
	v_fmac_f32_e32 v70, v76, v21
	v_fmac_f32_e32 v71, v76, v25
	v_fmac_f32_e32 v0, v75, v2
	v_fmac_f32_e32 v65, v75, v26
	v_fmac_f32_e32 v66, v75, v30
	v_fmac_f32_e32 v67, v75, v34
	v_fmac_f32_e32 v68, v75, v38
	s_waitcnt lgkmcnt(1)
	v_fmac_f32_e32 v69, v75, v42
	v_fmac_f32_e32 v70, v75, v46
	s_waitcnt lgkmcnt(0)
	v_fmac_f32_e32 v71, v75, v50
	v_fmac_f32_e32 v0, v74, v3
	v_fmac_f32_e32 v65, v74, v27
	v_fmac_f32_e32 v66, v74, v31
	v_fmac_f32_e32 v67, v74, v35
	v_fmac_f32_e32 v68, v74, v39
	v_fmac_f32_e32 v69, v74, v43
	v_fmac_f32_e32 v70, v74, v47
	v_fmac_f32_e32 v71, v74, v51
	v_fmac_f32_e32 v0, v72, v4
	v_fmac_f32_e32 v65, v72, v28
	v_fmac_f32_e32 v66, v72, v32
	v_fmac_f32_e32 v67, v72, v36
	v_fmac_f32_e32 v68, v72, v40
	v_fmac_f32_e32 v69, v72, v44
	v_fmac_f32_e32 v70, v72, v48
	v_fmac_f32_e32 v71, v72, v52
	v_add_u32_e32 v64, 64, v64
	v_fmac_f32_e32 v0, v73, v5
	v_fmac_f32_e32 v65, v73, v29
	v_fmac_f32_e32 v66, v73, v33
	v_fmac_f32_e32 v67, v73, v37
	v_fmac_f32_e32 v68, v73, v41
	v_fmac_f32_e32 v69, v73, v45
	v_fmac_f32_e32 v70, v73, v49
	v_fmac_f32_e32 v71, v73, v53
	v_lshl_add_u64 v[18:19], v[60:61], 0, s[20:21]
	v_add_co_u32_e64 v20, s[0:1], s29, v18
	ds_read_b128 v[72:75], v64
	ds_read_b128 v[6:9], v64 offset:16
	ds_read_b128 v[22:25], v64 offset:4096
	ds_read_b128 v[14:17], v64 offset:8192
	ds_read_b128 v[10:13], v64 offset:12288
	ds_read_b128 v[2:5], v64 offset:16384
	v_addc_co_u32_e64 v21, s[0:1], 0, v19, s[0:1]
	v_add_co_u32_e64 v26, s[0:1], s5, v18
	s_add_u32 s20, s20, 0x30000
	s_nop 0
	v_addc_co_u32_e64 v27, s[0:1], 0, v19, s[0:1]
	s_mov_b32 s0, 0x9000
	s_nop 0
	v_add_co_u32_e64 v46, s[0:1], s0, v18
	v_mov_b32_e32 v50, v124
	v_mov_b32_e32 v51, v125
	v_mov_b32_e32 v52, v126
	v_addc_co_u32_e64 v47, s[0:1], 0, v19, s[0:1]
	v_add_co_u32_e64 v48, s[0:1], s50, v18
	ds_read_b128 v[26:29], v64 offset:20480
	s_nop 0
	v_addc_co_u32_e64 v49, s[0:1], 0, v19, s[0:1]
	s_mov_b32 s0, 0xf000
	s_nop 0
	v_add_co_u32_e64 v76, s[0:1], s0, v18
	s_addc_u32 s21, s21, 0
	s_nop 0
	v_addc_co_u32_e64 v77, s[0:1], 0, v19, s[0:1]
	s_mov_b32 s0, 0x12000
	s_nop 0
	v_add_co_u32_e64 v78, s[0:1], s0, v18
	s_cmp_eq_u32 s20, 0xc0000
	s_nop 0
	v_addc_co_u32_e64 v79, s[0:1], 0, v19, s[0:1]
	v_mov_b32_e32 v53, v127
	s_nop 0
	v_mov_b32_e32 v49, v128
	s_nop 0
	v_mov_b32_e32 v48, v129
	v_mov_b32_e32 v47, v130
	s_mov_b32 s0, 0x15000
	v_add_co_u32_e64 v80, s[0:1], s0, v18
	ds_read_b128 v[82:85], v64 offset:12304
	ds_read_b128 v[86:89], v64 offset:16400
	v_addc_co_u32_e64 v81, s[0:1], 0, v19, s[0:1]
	v_add_co_u32_e64 v30, s[0:1], s96, v18
	v_mov_b32_e32 v46, v131
	s_nop 0
	v_addc_co_u32_e64 v31, s[0:1], 0, v19, s[0:1]
	s_mov_b32 s0, 0x1b000
	s_nop 0
	v_add_co_u32_e64 v34, s[0:1], s0, v18
	ds_read_b128 v[78:81], v64 offset:4112
	s_nop 0
	v_addc_co_u32_e64 v35, s[0:1], 0, v19, s[0:1]
	s_mov_b32 s0, 0x1e000
	s_nop 0
	v_add_co_u32_e64 v40, s[0:1], s0, v18
	ds_read_b128 v[90:93], v64 offset:20496
	s_nop 0
	v_addc_co_u32_e64 v41, s[0:1], 0, v19, s[0:1]
	s_mov_b32 s0, 0x21000
	s_nop 0
	v_add_co_u32_e64 v32, s[0:1], s0, v18
	ds_read_b128 v[94:97], v64 offset:24592
	s_nop 0
	v_addc_co_u32_e64 v33, s[0:1], 0, v19, s[0:1]
	s_mov_b32 s0, 0x24000
	s_nop 0
	v_add_co_u32_e64 v38, s[0:1], s0, v18
	s_waitcnt lgkmcnt(9)
	v_fmac_f32_e32 v65, v50, v22
	v_addc_co_u32_e64 v39, s[0:1], 0, v19, s[0:1]
	s_mov_b32 s0, 0x27000
	s_nop 0
	v_add_co_u32_e64 v42, s[0:1], s0, v18
	s_waitcnt lgkmcnt(6)
	v_fmac_f32_e32 v68, v50, v2
	v_addc_co_u32_e64 v43, s[0:1], 0, v19, s[0:1]
	s_mov_b32 s0, 0x2a000
	s_nop 0
	v_add_co_u32_e64 v44, s[0:1], s0, v18
	v_fmac_f32_e32 v65, v51, v23
	v_addc_co_u32_e64 v45, s[0:1], 0, v19, s[0:1]
	s_mov_b32 s0, 0x2d000
	s_nop 0
	v_add_co_u32_e64 v36, s[0:1], s0, v18
	v_fmac_f32_e32 v68, v51, v3
	s_nop 0
	v_addc_co_u32_e64 v37, s[0:1], 0, v19, s[0:1]
	ds_read_b128 v[18:21], v64 offset:24576
	v_fmac_f32_e32 v65, v52, v24
	v_fmac_f32_e32 v68, v52, v4
	v_fmac_f32_e32 v65, v53, v25
	ds_read_b128 v[22:25], v64 offset:8208
	v_fmac_f32_e32 v68, v53, v5
	ds_read_b128 v[2:5], v64 offset:28672
	ds_read_b128 v[98:101], v64 offset:28688
	v_fmac_f32_e32 v0, v50, v72
	v_fmac_f32_e32 v66, v50, v14
	v_fmac_f32_e32 v67, v50, v10
	s_waitcnt lgkmcnt(9)
	v_fmac_f32_e32 v69, v50, v26
	s_waitcnt lgkmcnt(3)
	v_fmac_f32_e32 v70, v50, v18
	s_waitcnt lgkmcnt(1)
	v_fmac_f32_e32 v71, v50, v2
	v_fmac_f32_e32 v0, v51, v73
	v_fmac_f32_e32 v66, v51, v15
	v_fmac_f32_e32 v67, v51, v11
	v_fmac_f32_e32 v69, v51, v27
	v_fmac_f32_e32 v70, v51, v19
	v_fmac_f32_e32 v71, v51, v3
	v_fmac_f32_e32 v0, v52, v74
	v_fmac_f32_e32 v66, v52, v16
	v_fmac_f32_e32 v67, v52, v12
	v_fmac_f32_e32 v69, v52, v28
	v_fmac_f32_e32 v70, v52, v20
	v_fmac_f32_e32 v71, v52, v4
	v_fmac_f32_e32 v0, v53, v75
	v_fmac_f32_e32 v66, v53, v17
	v_fmac_f32_e32 v67, v53, v13
	v_fmac_f32_e32 v69, v53, v29
	v_fmac_f32_e32 v70, v53, v21
	v_fmac_f32_e32 v71, v53, v5
	ds_read_b128 v[50:53], v64 offset:32
	v_mov_b32_e32 v77, v132
	v_mov_b32_e32 v106, v133
	v_mov_b32_e32 v107, v134
	ds_read_b128 v[2:5], v64 offset:48
	v_mov_b32_e32 v76, v135
	v_mov_b32_e32 v75, v136
	v_mov_b32_e32 v74, v137
	v_mov_b32_e32 v72, v138
	v_mov_b32_e32 v73, v139
	ds_read_b128 v[42:45], v64 offset:4128
	ds_read_b128 v[26:29], v64 offset:4144
	v_fmac_f32_e32 v0, v49, v6
	v_fmac_f32_e32 v65, v49, v78
	v_fmac_f32_e32 v66, v49, v22
	v_fmac_f32_e32 v0, v48, v7
	v_fmac_f32_e32 v65, v48, v79
	v_fmac_f32_e32 v66, v48, v23
	v_fmac_f32_e32 v0, v47, v8
	v_fmac_f32_e32 v65, v47, v80
	v_fmac_f32_e32 v66, v47, v24
	ds_read_b128 v[102:105], v64 offset:8224
	ds_read_b128 v[30:33], v64 offset:8240
	v_fmac_f32_e32 v0, v46, v9
	ds_read_b128 v[6:9], v64 offset:12320
	ds_read_b128 v[34:37], v64 offset:12336
	v_fmac_f32_e32 v65, v46, v81
	ds_read_b128 v[10:13], v64 offset:16416
	ds_read_b128 v[38:41], v64 offset:16432
	v_fmac_f32_e32 v66, v46, v25
	ds_read_b128 v[14:17], v64 offset:20512
	ds_read_b128 v[18:21], v64 offset:24608
	ds_read_b128 v[22:25], v64 offset:28704
	v_fmac_f32_e32 v67, v49, v82
	v_fmac_f32_e32 v68, v49, v86
	v_fmac_f32_e32 v69, v49, v90
	v_fmac_f32_e32 v70, v49, v94
	s_waitcnt lgkmcnt(13)
	v_fmac_f32_e32 v71, v49, v98
	v_fmac_f32_e32 v67, v48, v83
	v_fmac_f32_e32 v68, v48, v87
	v_fmac_f32_e32 v69, v48, v91
	v_fmac_f32_e32 v70, v48, v95
	v_fmac_f32_e32 v71, v48, v99
	v_fmac_f32_e32 v67, v47, v84
	v_fmac_f32_e32 v68, v47, v88
	v_fmac_f32_e32 v69, v47, v92
	v_fmac_f32_e32 v70, v47, v96
	v_fmac_f32_e32 v71, v47, v100
	v_fmac_f32_e32 v67, v46, v85
	v_fmac_f32_e32 v68, v46, v89
	v_fmac_f32_e32 v69, v46, v93
	v_fmac_f32_e32 v70, v46, v97
	v_fmac_f32_e32 v71, v46, v101
	ds_read_b128 v[46:49], v64 offset:24624
	s_waitcnt lgkmcnt(13)
	v_fmac_f32_e32 v0, v77, v50
	s_waitcnt lgkmcnt(11)
	v_fmac_f32_e32 v65, v77, v42
	v_fmac_f32_e32 v0, v106, v51
	v_fmac_f32_e32 v65, v106, v43
	v_fmac_f32_e32 v0, v107, v52
	v_fmac_f32_e32 v65, v107, v44
	v_fmac_f32_e32 v0, v76, v53
	v_fmac_f32_e32 v65, v76, v45
	ds_read_b128 v[42:45], v64 offset:20528
	ds_read_b128 v[50:53], v64 offset:28720
	s_waitcnt lgkmcnt(11)
	v_fmac_f32_e32 v66, v77, v102
	s_waitcnt lgkmcnt(9)
	v_fmac_f32_e32 v67, v77, v6
	s_waitcnt lgkmcnt(7)
	v_fmac_f32_e32 v68, v77, v10
	s_waitcnt lgkmcnt(5)
	v_fmac_f32_e32 v69, v77, v14
	s_waitcnt lgkmcnt(4)
	v_fmac_f32_e32 v70, v77, v18
	s_waitcnt lgkmcnt(3)
	v_fmac_f32_e32 v71, v77, v22
	v_fmac_f32_e32 v66, v106, v103
	v_fmac_f32_e32 v67, v106, v7
	v_fmac_f32_e32 v68, v106, v11
	v_fmac_f32_e32 v69, v106, v15
	v_fmac_f32_e32 v70, v106, v19
	v_fmac_f32_e32 v71, v106, v23
	v_fmac_f32_e32 v66, v107, v104
	v_fmac_f32_e32 v67, v107, v8
	v_fmac_f32_e32 v68, v107, v12
	v_fmac_f32_e32 v69, v107, v16
	v_fmac_f32_e32 v70, v107, v20
	v_fmac_f32_e32 v71, v107, v24
	v_fmac_f32_e32 v66, v76, v105
	v_fmac_f32_e32 v67, v76, v9
	v_fmac_f32_e32 v68, v76, v13
	v_fmac_f32_e32 v69, v76, v17
	v_fmac_f32_e32 v70, v76, v21
	v_fmac_f32_e32 v71, v76, v25
	v_fmac_f32_e32 v0, v75, v2
	v_fmac_f32_e32 v65, v75, v26
	v_fmac_f32_e32 v66, v75, v30
	v_fmac_f32_e32 v67, v75, v34
	v_fmac_f32_e32 v68, v75, v38
	s_waitcnt lgkmcnt(1)
	v_fmac_f32_e32 v69, v75, v42
	v_fmac_f32_e32 v70, v75, v46
	s_waitcnt lgkmcnt(0)
	v_fmac_f32_e32 v71, v75, v50
	v_fmac_f32_e32 v0, v74, v3
	v_fmac_f32_e32 v65, v74, v27
	v_fmac_f32_e32 v66, v74, v31
	v_fmac_f32_e32 v67, v74, v35
	v_fmac_f32_e32 v68, v74, v39
	v_fmac_f32_e32 v69, v74, v43
	v_fmac_f32_e32 v70, v74, v47
	v_fmac_f32_e32 v71, v74, v51
	v_fmac_f32_e32 v0, v72, v4
	v_fmac_f32_e32 v65, v72, v28
	v_fmac_f32_e32 v66, v72, v32
	v_fmac_f32_e32 v67, v72, v36
	v_fmac_f32_e32 v68, v72, v40
	v_fmac_f32_e32 v69, v72, v44
	v_fmac_f32_e32 v70, v72, v48
	v_fmac_f32_e32 v71, v72, v52
	v_add_u32_e32 v64, 64, v64
	v_fmac_f32_e32 v0, v73, v5
	v_fmac_f32_e32 v65, v73, v29
	v_fmac_f32_e32 v66, v73, v33
	v_fmac_f32_e32 v67, v73, v37
	v_fmac_f32_e32 v68, v73, v41
	v_fmac_f32_e32 v69, v73, v45
	v_fmac_f32_e32 v70, v73, v49
	v_fmac_f32_e32 v71, v73, v53
	v_lshl_add_u64 v[18:19], v[60:61], 0, s[20:21]
	v_add_co_u32_e64 v20, s[0:1], s29, v18
	ds_read_b128 v[72:75], v64
	ds_read_b128 v[6:9], v64 offset:16
	ds_read_b128 v[22:25], v64 offset:4096
	ds_read_b128 v[14:17], v64 offset:8192
	ds_read_b128 v[10:13], v64 offset:12288
	ds_read_b128 v[2:5], v64 offset:16384
	v_addc_co_u32_e64 v21, s[0:1], 0, v19, s[0:1]
	v_add_co_u32_e64 v26, s[0:1], s5, v18
	s_add_u32 s20, s20, 0x30000
	s_nop 0
	v_addc_co_u32_e64 v27, s[0:1], 0, v19, s[0:1]
	s_mov_b32 s0, 0x9000
	s_nop 0
	v_add_co_u32_e64 v46, s[0:1], s0, v18
	v_mov_b32_e32 v50, v140
	v_mov_b32_e32 v51, v141
	v_mov_b32_e32 v52, v142
	v_addc_co_u32_e64 v47, s[0:1], 0, v19, s[0:1]
	v_add_co_u32_e64 v48, s[0:1], s50, v18
	ds_read_b128 v[26:29], v64 offset:20480
	s_nop 0
	v_addc_co_u32_e64 v49, s[0:1], 0, v19, s[0:1]
	s_mov_b32 s0, 0xf000
	s_nop 0
	v_add_co_u32_e64 v76, s[0:1], s0, v18
	s_addc_u32 s21, s21, 0
	s_nop 0
	v_addc_co_u32_e64 v77, s[0:1], 0, v19, s[0:1]
	s_mov_b32 s0, 0x12000
	s_nop 0
	v_add_co_u32_e64 v78, s[0:1], s0, v18
	s_cmp_eq_u32 s20, 0xc0000
	s_nop 0
	v_addc_co_u32_e64 v79, s[0:1], 0, v19, s[0:1]
	v_mov_b32_e32 v53, v143
	s_nop 0
	v_mov_b32_e32 v49, v144
	s_nop 0
	v_mov_b32_e32 v48, v145
	v_mov_b32_e32 v47, v146
	s_mov_b32 s0, 0x15000
	v_add_co_u32_e64 v80, s[0:1], s0, v18
	ds_read_b128 v[82:85], v64 offset:12304
	ds_read_b128 v[86:89], v64 offset:16400
	v_addc_co_u32_e64 v81, s[0:1], 0, v19, s[0:1]
	v_add_co_u32_e64 v30, s[0:1], s96, v18
	v_mov_b32_e32 v46, v147
	s_nop 0
	v_addc_co_u32_e64 v31, s[0:1], 0, v19, s[0:1]
	s_mov_b32 s0, 0x1b000
	s_nop 0
	v_add_co_u32_e64 v34, s[0:1], s0, v18
	ds_read_b128 v[78:81], v64 offset:4112
	s_nop 0
	v_addc_co_u32_e64 v35, s[0:1], 0, v19, s[0:1]
	s_mov_b32 s0, 0x1e000
	s_nop 0
	v_add_co_u32_e64 v40, s[0:1], s0, v18
	ds_read_b128 v[90:93], v64 offset:20496
	s_nop 0
	v_addc_co_u32_e64 v41, s[0:1], 0, v19, s[0:1]
	s_mov_b32 s0, 0x21000
	s_nop 0
	v_add_co_u32_e64 v32, s[0:1], s0, v18
	ds_read_b128 v[94:97], v64 offset:24592
	s_nop 0
	v_addc_co_u32_e64 v33, s[0:1], 0, v19, s[0:1]
	s_mov_b32 s0, 0x24000
	s_nop 0
	v_add_co_u32_e64 v38, s[0:1], s0, v18
	s_waitcnt lgkmcnt(9)
	v_fmac_f32_e32 v65, v50, v22
	v_addc_co_u32_e64 v39, s[0:1], 0, v19, s[0:1]
	s_mov_b32 s0, 0x27000
	s_nop 0
	v_add_co_u32_e64 v42, s[0:1], s0, v18
	s_waitcnt lgkmcnt(6)
	v_fmac_f32_e32 v68, v50, v2
	v_addc_co_u32_e64 v43, s[0:1], 0, v19, s[0:1]
	s_mov_b32 s0, 0x2a000
	s_nop 0
	v_add_co_u32_e64 v44, s[0:1], s0, v18
	v_fmac_f32_e32 v65, v51, v23
	v_addc_co_u32_e64 v45, s[0:1], 0, v19, s[0:1]
	s_mov_b32 s0, 0x2d000
	s_nop 0
	v_add_co_u32_e64 v36, s[0:1], s0, v18
	v_fmac_f32_e32 v68, v51, v3
	s_nop 0
	v_addc_co_u32_e64 v37, s[0:1], 0, v19, s[0:1]
	ds_read_b128 v[18:21], v64 offset:24576
	v_fmac_f32_e32 v65, v52, v24
	v_fmac_f32_e32 v68, v52, v4
	v_fmac_f32_e32 v65, v53, v25
	ds_read_b128 v[22:25], v64 offset:8208
	v_fmac_f32_e32 v68, v53, v5
	ds_read_b128 v[2:5], v64 offset:28672
	ds_read_b128 v[98:101], v64 offset:28688
	v_fmac_f32_e32 v0, v50, v72
	v_fmac_f32_e32 v66, v50, v14
	v_fmac_f32_e32 v67, v50, v10
	s_waitcnt lgkmcnt(9)
	v_fmac_f32_e32 v69, v50, v26
	s_waitcnt lgkmcnt(3)
	v_fmac_f32_e32 v70, v50, v18
	s_waitcnt lgkmcnt(1)
	v_fmac_f32_e32 v71, v50, v2
	v_fmac_f32_e32 v0, v51, v73
	v_fmac_f32_e32 v66, v51, v15
	v_fmac_f32_e32 v67, v51, v11
	v_fmac_f32_e32 v69, v51, v27
	v_fmac_f32_e32 v70, v51, v19
	v_fmac_f32_e32 v71, v51, v3
	v_fmac_f32_e32 v0, v52, v74
	v_fmac_f32_e32 v66, v52, v16
	v_fmac_f32_e32 v67, v52, v12
	v_fmac_f32_e32 v69, v52, v28
	v_fmac_f32_e32 v70, v52, v20
	v_fmac_f32_e32 v71, v52, v4
	v_fmac_f32_e32 v0, v53, v75
	v_fmac_f32_e32 v66, v53, v17
	v_fmac_f32_e32 v67, v53, v13
	v_fmac_f32_e32 v69, v53, v29
	v_fmac_f32_e32 v70, v53, v21
	v_fmac_f32_e32 v71, v53, v5
	ds_read_b128 v[50:53], v64 offset:32
	v_mov_b32_e32 v77, v148
	v_mov_b32_e32 v106, v149
	v_mov_b32_e32 v107, v150
	ds_read_b128 v[2:5], v64 offset:48
	v_mov_b32_e32 v76, v151
	v_mov_b32_e32 v75, v152
	v_mov_b32_e32 v74, v153
	v_mov_b32_e32 v72, v154
	v_mov_b32_e32 v73, v155
	ds_read_b128 v[42:45], v64 offset:4128
	ds_read_b128 v[26:29], v64 offset:4144
	v_fmac_f32_e32 v0, v49, v6
	v_fmac_f32_e32 v65, v49, v78
	v_fmac_f32_e32 v66, v49, v22
	v_fmac_f32_e32 v0, v48, v7
	v_fmac_f32_e32 v65, v48, v79
	v_fmac_f32_e32 v66, v48, v23
	v_fmac_f32_e32 v0, v47, v8
	v_fmac_f32_e32 v65, v47, v80
	v_fmac_f32_e32 v66, v47, v24
	ds_read_b128 v[102:105], v64 offset:8224
	ds_read_b128 v[30:33], v64 offset:8240
	v_fmac_f32_e32 v0, v46, v9
	ds_read_b128 v[6:9], v64 offset:12320
	ds_read_b128 v[34:37], v64 offset:12336
	v_fmac_f32_e32 v65, v46, v81
	ds_read_b128 v[10:13], v64 offset:16416
	ds_read_b128 v[38:41], v64 offset:16432
	v_fmac_f32_e32 v66, v46, v25
	ds_read_b128 v[14:17], v64 offset:20512
	ds_read_b128 v[18:21], v64 offset:24608
	ds_read_b128 v[22:25], v64 offset:28704
	v_fmac_f32_e32 v67, v49, v82
	v_fmac_f32_e32 v68, v49, v86
	v_fmac_f32_e32 v69, v49, v90
	v_fmac_f32_e32 v70, v49, v94
	s_waitcnt lgkmcnt(13)
	v_fmac_f32_e32 v71, v49, v98
	v_fmac_f32_e32 v67, v48, v83
	v_fmac_f32_e32 v68, v48, v87
	v_fmac_f32_e32 v69, v48, v91
	v_fmac_f32_e32 v70, v48, v95
	v_fmac_f32_e32 v71, v48, v99
	v_fmac_f32_e32 v67, v47, v84
	v_fmac_f32_e32 v68, v47, v88
	v_fmac_f32_e32 v69, v47, v92
	v_fmac_f32_e32 v70, v47, v96
	v_fmac_f32_e32 v71, v47, v100
	v_fmac_f32_e32 v67, v46, v85
	v_fmac_f32_e32 v68, v46, v89
	v_fmac_f32_e32 v69, v46, v93
	v_fmac_f32_e32 v70, v46, v97
	v_fmac_f32_e32 v71, v46, v101
	ds_read_b128 v[46:49], v64 offset:24624
	s_waitcnt lgkmcnt(13)
	v_fmac_f32_e32 v0, v77, v50
	s_waitcnt lgkmcnt(11)
	v_fmac_f32_e32 v65, v77, v42
	v_fmac_f32_e32 v0, v106, v51
	v_fmac_f32_e32 v65, v106, v43
	v_fmac_f32_e32 v0, v107, v52
	v_fmac_f32_e32 v65, v107, v44
	v_fmac_f32_e32 v0, v76, v53
	v_fmac_f32_e32 v65, v76, v45
	ds_read_b128 v[42:45], v64 offset:20528
	ds_read_b128 v[50:53], v64 offset:28720
	s_waitcnt lgkmcnt(11)
	v_fmac_f32_e32 v66, v77, v102
	s_waitcnt lgkmcnt(9)
	v_fmac_f32_e32 v67, v77, v6
	s_waitcnt lgkmcnt(7)
	v_fmac_f32_e32 v68, v77, v10
	s_waitcnt lgkmcnt(5)
	v_fmac_f32_e32 v69, v77, v14
	s_waitcnt lgkmcnt(4)
	v_fmac_f32_e32 v70, v77, v18
	s_waitcnt lgkmcnt(3)
	v_fmac_f32_e32 v71, v77, v22
	v_fmac_f32_e32 v66, v106, v103
	v_fmac_f32_e32 v67, v106, v7
	v_fmac_f32_e32 v68, v106, v11
	v_fmac_f32_e32 v69, v106, v15
	v_fmac_f32_e32 v70, v106, v19
	v_fmac_f32_e32 v71, v106, v23
	v_fmac_f32_e32 v66, v107, v104
	v_fmac_f32_e32 v67, v107, v8
	v_fmac_f32_e32 v68, v107, v12
	v_fmac_f32_e32 v69, v107, v16
	v_fmac_f32_e32 v70, v107, v20
	v_fmac_f32_e32 v71, v107, v24
	v_fmac_f32_e32 v66, v76, v105
	v_fmac_f32_e32 v67, v76, v9
	v_fmac_f32_e32 v68, v76, v13
	v_fmac_f32_e32 v69, v76, v17
	v_fmac_f32_e32 v70, v76, v21
	v_fmac_f32_e32 v71, v76, v25
	v_fmac_f32_e32 v0, v75, v2
	v_fmac_f32_e32 v65, v75, v26
	v_fmac_f32_e32 v66, v75, v30
	v_fmac_f32_e32 v67, v75, v34
	v_fmac_f32_e32 v68, v75, v38
	s_waitcnt lgkmcnt(1)
	v_fmac_f32_e32 v69, v75, v42
	v_fmac_f32_e32 v70, v75, v46
	s_waitcnt lgkmcnt(0)
	v_fmac_f32_e32 v71, v75, v50
	v_fmac_f32_e32 v0, v74, v3
	v_fmac_f32_e32 v65, v74, v27
	v_fmac_f32_e32 v66, v74, v31
	v_fmac_f32_e32 v67, v74, v35
	v_fmac_f32_e32 v68, v74, v39
	v_fmac_f32_e32 v69, v74, v43
	v_fmac_f32_e32 v70, v74, v47
	v_fmac_f32_e32 v71, v74, v51
	v_fmac_f32_e32 v0, v72, v4
	v_fmac_f32_e32 v65, v72, v28
	v_fmac_f32_e32 v66, v72, v32
	v_fmac_f32_e32 v67, v72, v36
	v_fmac_f32_e32 v68, v72, v40
	v_fmac_f32_e32 v69, v72, v44
	v_fmac_f32_e32 v70, v72, v48
	v_fmac_f32_e32 v71, v72, v52
	v_add_u32_e32 v64, 64, v64
	v_fmac_f32_e32 v0, v73, v5
	v_fmac_f32_e32 v65, v73, v29
	v_fmac_f32_e32 v66, v73, v33
	v_fmac_f32_e32 v67, v73, v37
	v_fmac_f32_e32 v68, v73, v41
	v_fmac_f32_e32 v69, v73, v45
	v_fmac_f32_e32 v70, v73, v49
	v_fmac_f32_e32 v71, v73, v53
	v_lshl_add_u64 v[18:19], v[60:61], 0, s[20:21]
	v_add_co_u32_e64 v20, s[0:1], s29, v18
	ds_read_b128 v[72:75], v64
	ds_read_b128 v[6:9], v64 offset:16
	ds_read_b128 v[22:25], v64 offset:4096
	ds_read_b128 v[14:17], v64 offset:8192
	ds_read_b128 v[10:13], v64 offset:12288
	ds_read_b128 v[2:5], v64 offset:16384
	v_addc_co_u32_e64 v21, s[0:1], 0, v19, s[0:1]
	v_add_co_u32_e64 v26, s[0:1], s5, v18
	s_add_u32 s20, s20, 0x30000
	s_nop 0
	v_addc_co_u32_e64 v27, s[0:1], 0, v19, s[0:1]
	s_mov_b32 s0, 0x9000
	s_nop 0
	v_add_co_u32_e64 v46, s[0:1], s0, v18
	v_mov_b32_e32 v50, v156
	v_mov_b32_e32 v51, v157
	v_mov_b32_e32 v52, v158
	v_addc_co_u32_e64 v47, s[0:1], 0, v19, s[0:1]
	v_add_co_u32_e64 v48, s[0:1], s50, v18
	ds_read_b128 v[26:29], v64 offset:20480
	s_nop 0
	v_addc_co_u32_e64 v49, s[0:1], 0, v19, s[0:1]
	s_mov_b32 s0, 0xf000
	s_nop 0
	v_add_co_u32_e64 v76, s[0:1], s0, v18
	s_addc_u32 s21, s21, 0
	s_nop 0
	v_addc_co_u32_e64 v77, s[0:1], 0, v19, s[0:1]
	s_mov_b32 s0, 0x12000
	s_nop 0
	v_add_co_u32_e64 v78, s[0:1], s0, v18
	s_cmp_eq_u32 s20, 0xc0000
	s_nop 0
	v_addc_co_u32_e64 v79, s[0:1], 0, v19, s[0:1]
	v_mov_b32_e32 v53, v159
	s_nop 0
	v_mov_b32_e32 v49, v160
	s_nop 0
	v_mov_b32_e32 v48, v161
	v_mov_b32_e32 v47, v162
	s_mov_b32 s0, 0x15000
	v_add_co_u32_e64 v80, s[0:1], s0, v18
	ds_read_b128 v[82:85], v64 offset:12304
	ds_read_b128 v[86:89], v64 offset:16400
	v_addc_co_u32_e64 v81, s[0:1], 0, v19, s[0:1]
	v_add_co_u32_e64 v30, s[0:1], s96, v18
	v_mov_b32_e32 v46, v163
	s_nop 0
	v_addc_co_u32_e64 v31, s[0:1], 0, v19, s[0:1]
	s_mov_b32 s0, 0x1b000
	s_nop 0
	v_add_co_u32_e64 v34, s[0:1], s0, v18
	ds_read_b128 v[78:81], v64 offset:4112
	s_nop 0
	v_addc_co_u32_e64 v35, s[0:1], 0, v19, s[0:1]
	s_mov_b32 s0, 0x1e000
	s_nop 0
	v_add_co_u32_e64 v40, s[0:1], s0, v18
	ds_read_b128 v[90:93], v64 offset:20496
	s_nop 0
	v_addc_co_u32_e64 v41, s[0:1], 0, v19, s[0:1]
	s_mov_b32 s0, 0x21000
	s_nop 0
	v_add_co_u32_e64 v32, s[0:1], s0, v18
	ds_read_b128 v[94:97], v64 offset:24592
	s_nop 0
	v_addc_co_u32_e64 v33, s[0:1], 0, v19, s[0:1]
	s_mov_b32 s0, 0x24000
	s_nop 0
	v_add_co_u32_e64 v38, s[0:1], s0, v18
	s_waitcnt lgkmcnt(9)
	v_fmac_f32_e32 v65, v50, v22
	v_addc_co_u32_e64 v39, s[0:1], 0, v19, s[0:1]
	s_mov_b32 s0, 0x27000
	s_nop 0
	v_add_co_u32_e64 v42, s[0:1], s0, v18
	s_waitcnt lgkmcnt(6)
	v_fmac_f32_e32 v68, v50, v2
	v_addc_co_u32_e64 v43, s[0:1], 0, v19, s[0:1]
	s_mov_b32 s0, 0x2a000
	s_nop 0
	v_add_co_u32_e64 v44, s[0:1], s0, v18
	v_fmac_f32_e32 v65, v51, v23
	v_addc_co_u32_e64 v45, s[0:1], 0, v19, s[0:1]
	s_mov_b32 s0, 0x2d000
	s_nop 0
	v_add_co_u32_e64 v36, s[0:1], s0, v18
	v_fmac_f32_e32 v68, v51, v3
	s_nop 0
	v_addc_co_u32_e64 v37, s[0:1], 0, v19, s[0:1]
	ds_read_b128 v[18:21], v64 offset:24576
	v_fmac_f32_e32 v65, v52, v24
	v_fmac_f32_e32 v68, v52, v4
	v_fmac_f32_e32 v65, v53, v25
	ds_read_b128 v[22:25], v64 offset:8208
	v_fmac_f32_e32 v68, v53, v5
	ds_read_b128 v[2:5], v64 offset:28672
	ds_read_b128 v[98:101], v64 offset:28688
	v_fmac_f32_e32 v0, v50, v72
	v_fmac_f32_e32 v66, v50, v14
	v_fmac_f32_e32 v67, v50, v10
	s_waitcnt lgkmcnt(9)
	v_fmac_f32_e32 v69, v50, v26
	s_waitcnt lgkmcnt(3)
	v_fmac_f32_e32 v70, v50, v18
	s_waitcnt lgkmcnt(1)
	v_fmac_f32_e32 v71, v50, v2
	v_fmac_f32_e32 v0, v51, v73
	v_fmac_f32_e32 v66, v51, v15
	v_fmac_f32_e32 v67, v51, v11
	v_fmac_f32_e32 v69, v51, v27
	v_fmac_f32_e32 v70, v51, v19
	v_fmac_f32_e32 v71, v51, v3
	v_fmac_f32_e32 v0, v52, v74
	v_fmac_f32_e32 v66, v52, v16
	v_fmac_f32_e32 v67, v52, v12
	v_fmac_f32_e32 v69, v52, v28
	v_fmac_f32_e32 v70, v52, v20
	v_fmac_f32_e32 v71, v52, v4
	v_fmac_f32_e32 v0, v53, v75
	v_fmac_f32_e32 v66, v53, v17
	v_fmac_f32_e32 v67, v53, v13
	v_fmac_f32_e32 v69, v53, v29
	v_fmac_f32_e32 v70, v53, v21
	v_fmac_f32_e32 v71, v53, v5
	ds_read_b128 v[50:53], v64 offset:32
	v_mov_b32_e32 v77, v164
	v_mov_b32_e32 v106, v165
	v_mov_b32_e32 v107, v166
	ds_read_b128 v[2:5], v64 offset:48
	v_mov_b32_e32 v76, v167
	v_mov_b32_e32 v75, v168
	v_mov_b32_e32 v74, v169
	v_mov_b32_e32 v72, v170
	v_mov_b32_e32 v73, v171
	ds_read_b128 v[42:45], v64 offset:4128
	ds_read_b128 v[26:29], v64 offset:4144
	v_fmac_f32_e32 v0, v49, v6
	v_fmac_f32_e32 v65, v49, v78
	v_fmac_f32_e32 v66, v49, v22
	v_fmac_f32_e32 v0, v48, v7
	v_fmac_f32_e32 v65, v48, v79
	v_fmac_f32_e32 v66, v48, v23
	v_fmac_f32_e32 v0, v47, v8
	v_fmac_f32_e32 v65, v47, v80
	v_fmac_f32_e32 v66, v47, v24
	ds_read_b128 v[102:105], v64 offset:8224
	ds_read_b128 v[30:33], v64 offset:8240
	v_fmac_f32_e32 v0, v46, v9
	ds_read_b128 v[6:9], v64 offset:12320
	ds_read_b128 v[34:37], v64 offset:12336
	v_fmac_f32_e32 v65, v46, v81
	ds_read_b128 v[10:13], v64 offset:16416
	ds_read_b128 v[38:41], v64 offset:16432
	v_fmac_f32_e32 v66, v46, v25
	ds_read_b128 v[14:17], v64 offset:20512
	ds_read_b128 v[18:21], v64 offset:24608
	ds_read_b128 v[22:25], v64 offset:28704
	v_fmac_f32_e32 v67, v49, v82
	v_fmac_f32_e32 v68, v49, v86
	v_fmac_f32_e32 v69, v49, v90
	v_fmac_f32_e32 v70, v49, v94
	s_waitcnt lgkmcnt(13)
	v_fmac_f32_e32 v71, v49, v98
	v_fmac_f32_e32 v67, v48, v83
	v_fmac_f32_e32 v68, v48, v87
	v_fmac_f32_e32 v69, v48, v91
	v_fmac_f32_e32 v70, v48, v95
	v_fmac_f32_e32 v71, v48, v99
	v_fmac_f32_e32 v67, v47, v84
	v_fmac_f32_e32 v68, v47, v88
	v_fmac_f32_e32 v69, v47, v92
	v_fmac_f32_e32 v70, v47, v96
	v_fmac_f32_e32 v71, v47, v100
	v_fmac_f32_e32 v67, v46, v85
	v_fmac_f32_e32 v68, v46, v89
	v_fmac_f32_e32 v69, v46, v93
	v_fmac_f32_e32 v70, v46, v97
	v_fmac_f32_e32 v71, v46, v101
	ds_read_b128 v[46:49], v64 offset:24624
	s_waitcnt lgkmcnt(13)
	v_fmac_f32_e32 v0, v77, v50
	s_waitcnt lgkmcnt(11)
	v_fmac_f32_e32 v65, v77, v42
	v_fmac_f32_e32 v0, v106, v51
	v_fmac_f32_e32 v65, v106, v43
	v_fmac_f32_e32 v0, v107, v52
	v_fmac_f32_e32 v65, v107, v44
	v_fmac_f32_e32 v0, v76, v53
	v_fmac_f32_e32 v65, v76, v45
	ds_read_b128 v[42:45], v64 offset:20528
	ds_read_b128 v[50:53], v64 offset:28720
	s_waitcnt lgkmcnt(11)
	v_fmac_f32_e32 v66, v77, v102
	s_waitcnt lgkmcnt(9)
	v_fmac_f32_e32 v67, v77, v6
	s_waitcnt lgkmcnt(7)
	v_fmac_f32_e32 v68, v77, v10
	s_waitcnt lgkmcnt(5)
	v_fmac_f32_e32 v69, v77, v14
	s_waitcnt lgkmcnt(4)
	v_fmac_f32_e32 v70, v77, v18
	s_waitcnt lgkmcnt(3)
	v_fmac_f32_e32 v71, v77, v22
	v_fmac_f32_e32 v66, v106, v103
	v_fmac_f32_e32 v67, v106, v7
	v_fmac_f32_e32 v68, v106, v11
	v_fmac_f32_e32 v69, v106, v15
	v_fmac_f32_e32 v70, v106, v19
	v_fmac_f32_e32 v71, v106, v23
	v_fmac_f32_e32 v66, v107, v104
	v_fmac_f32_e32 v67, v107, v8
	v_fmac_f32_e32 v68, v107, v12
	v_fmac_f32_e32 v69, v107, v16
	v_fmac_f32_e32 v70, v107, v20
	v_fmac_f32_e32 v71, v107, v24
	v_fmac_f32_e32 v66, v76, v105
	v_fmac_f32_e32 v67, v76, v9
	v_fmac_f32_e32 v68, v76, v13
	v_fmac_f32_e32 v69, v76, v17
	v_fmac_f32_e32 v70, v76, v21
	v_fmac_f32_e32 v71, v76, v25
	v_fmac_f32_e32 v0, v75, v2
	v_fmac_f32_e32 v65, v75, v26
	v_fmac_f32_e32 v66, v75, v30
	v_fmac_f32_e32 v67, v75, v34
	v_fmac_f32_e32 v68, v75, v38
	s_waitcnt lgkmcnt(1)
	v_fmac_f32_e32 v69, v75, v42
	v_fmac_f32_e32 v70, v75, v46
	s_waitcnt lgkmcnt(0)
	v_fmac_f32_e32 v71, v75, v50
	v_fmac_f32_e32 v0, v74, v3
	v_fmac_f32_e32 v65, v74, v27
	v_fmac_f32_e32 v66, v74, v31
	v_fmac_f32_e32 v67, v74, v35
	v_fmac_f32_e32 v68, v74, v39
	v_fmac_f32_e32 v69, v74, v43
	v_fmac_f32_e32 v70, v74, v47
	v_fmac_f32_e32 v71, v74, v51
	v_fmac_f32_e32 v0, v72, v4
	v_fmac_f32_e32 v65, v72, v28
	v_fmac_f32_e32 v66, v72, v32
	v_fmac_f32_e32 v67, v72, v36
	v_fmac_f32_e32 v68, v72, v40
	v_fmac_f32_e32 v69, v72, v44
	v_fmac_f32_e32 v70, v72, v48
	v_fmac_f32_e32 v71, v72, v52
	v_add_u32_e32 v64, 64, v64
	v_fmac_f32_e32 v0, v73, v5
	v_fmac_f32_e32 v65, v73, v29
	v_fmac_f32_e32 v66, v73, v33
	v_fmac_f32_e32 v67, v73, v37
	v_fmac_f32_e32 v68, v73, v41
	v_fmac_f32_e32 v69, v73, v45
	v_fmac_f32_e32 v70, v73, v49
	v_fmac_f32_e32 v71, v73, v53
	v_add_u32_e32 v2, 0x8000, v62
	ds_write2_b32 v2, v0, v65 offset1:32
	ds_write2_b32 v2, v66, v67 offset0:64 offset1:96
	ds_write2_b32 v2, v68, v69 offset0:128 offset1:160
	ds_write2_b32 v2, v70, v71 offset0:192 offset1:224
	s_waitcnt lgkmcnt(0)
	s_barrier
	s_and_saveexec_b64 s[0:1], vcc
	s_cbranch_execz .LBB0_153
	s_mul_i32 s6, s10, 0xc00
	s_add_i32 s6, s6, s18
	v_or_b32_e32 v2, s6, v56
	v_readlane_b32 s52, v253, 15
	v_ashrrev_i32_e32 v3, 31, v2
	v_readlane_b32 s58, v253, 21
	v_readlane_b32 s59, v253, 22
	v_lshl_add_u32 v18, s10, 3, v55
	s_movk_i32 s6, 0xc00
	v_lshl_add_u64 v[2:3], v[2:3], 2, s[58:59]
	global_load_dword v0, v[2:3], off
	ds_read2st64_b32 v[2:3], v63 offset0:128 offset1:132
	ds_read2st64_b32 v[4:5], v63 offset0:136 offset1:140
	ds_read2st64_b32 v[6:7], v63 offset0:144 offset1:148
	ds_read2st64_b32 v[8:9], v63 offset0:152 offset1:156
	ds_read2st64_b32 v[10:11], v63 offset0:160 offset1:164
	ds_read2st64_b32 v[12:13], v63 offset0:168 offset1:172
	ds_read2st64_b32 v[14:15], v63 offset0:176 offset1:180
	ds_read2st64_b32 v[16:17], v63 offset0:184 offset1:188
	s_waitcnt lgkmcnt(7)
	v_add_f32_e32 v2, 0, v2
	v_add_f32_e32 v2, v2, v3
	s_waitcnt lgkmcnt(6)
	v_add_f32_e32 v2, v2, v4
	v_add_f32_e32 v2, v2, v5
	s_waitcnt lgkmcnt(5)
	v_add_f32_e32 v2, v2, v6
	v_add_f32_e32 v2, v2, v7
	s_waitcnt lgkmcnt(4)
	v_add_f32_e32 v2, v2, v8
	v_add_f32_e32 v2, v2, v9
	s_waitcnt lgkmcnt(3)
	v_add_f32_e32 v2, v2, v10
	v_add_f32_e32 v2, v2, v11
	s_waitcnt lgkmcnt(2)
	v_add_f32_e32 v2, v2, v12
	v_add_f32_e32 v2, v2, v13
	v_mul_lo_u32 v18, v18, s6
	s_waitcnt lgkmcnt(1)
	v_add_f32_e32 v2, v2, v14
	v_add_u32_e32 v18, s18, v18
	v_add_f32_e32 v2, v2, v15
	v_or_b32_e32 v18, v18, v56
	s_waitcnt lgkmcnt(0)
	v_add_f32_e32 v2, v2, v16
	v_readlane_b32 s61, v253, 24
	v_ashrrev_i32_e32 v19, 31, v18
	v_add_f32_e32 v2, v2, v17
	s_movk_i32 s61, 0xfff
	v_readlane_b32 s53, v253, 16
	v_readlane_b32 s54, v253, 17
	v_readlane_b32 s55, v253, 18
	v_readlane_b32 s56, v253, 19
	v_readlane_b32 s57, v253, 20
	v_readlane_b32 s60, v253, 23
	v_readlane_b32 s62, v253, 25
	v_readlane_b32 s63, v253, 26
	v_readlane_b32 s64, v253, 27
	v_readlane_b32 s65, v253, 28
	v_readlane_b32 s66, v253, 29
	v_readlane_b32 s67, v253, 30
	s_waitcnt vmcnt(0)
	v_add_f32_e32 v0, v2, v0
	v_lshl_add_u64 v[2:3], v[18:19], 2, s[22:23]
	global_store_dword v[2:3], v0, off sc1
	s_branch .LBB0_153

.LBB0_161:
	v_cmp_lt_i32_e32 vcc, s61, v19
	v_lshlrev_b32_e32 v0, 2, v2
	v_add_u32_e32 v7, 0x420, v18
	v_add_u32_e32 v20, 0x428, v18
	v_add_u32_e32 v21, 0x840, v18
	v_add_u32_e32 v22, 0x848, v18
	v_add_u32_e32 v23, 0xc60, v18
	v_add_u32_e32 v24, 0xc68, v18
	v_add_u32_e32 v25, 0x1080, v18
	v_add_u32_e32 v26, 0x1088, v18
	v_add_u32_e32 v27, 0x14a0, v18
	v_add_u32_e32 v28, 0x14a8, v18
	v_add_u32_e32 v29, 0x18c0, v18
	v_add_u32_e32 v30, 0x18c8, v18
	v_add_u32_e32 v31, 0x1ce0, v18
	v_add_u32_e32 v32, 0x1ce8, v18
	v_lshlrev_b32_e32 v6, 1, v4
	s_and_saveexec_b64 s[6:7], vcc
	s_xor_b64 s[20:21], exec, s[6:7]
	s_cbranch_execz .LBB0_163
	v_add_u32_e32 v33, 0xfffff000, v19
	v_lshrrev_b32_e32 v66, 10, v33
	v_mov_b32_e32 v67, v1
	v_lshlrev_b64 v[34:35], 23, v[66:67]
	v_and_b32_e32 v68, 0x3e0, v17
	v_lshl_add_u64 v[34:35], s[84:85], 0, v[34:35]
	v_and_b32_e32 v33, 0x7c0, v16
	v_lshlrev_b32_e32 v36, 2, v68
	v_mov_b32_e32 v37, v1
	v_or_b32_e32 v38, v33, v3
	v_lshl_add_u64 v[34:35], v[34:35], 0, v[36:37]
	v_lshl_add_u64 v[34:35], v[34:35], 0, v[0:1]
	v_lshlrev_b32_e32 v0, 12, v38
	v_lshl_add_u64 v[62:63], v[34:35], 0, v[0:1]
	v_add_co_u32_e32 v38, vcc, s97, v62
	s_mov_b32 s2, 0x20000
	s_nop 0
	v_addc_co_u32_e32 v39, vcc, 0, v63, vcc
	v_add_co_u32_e32 v42, vcc, s4, v62
	global_load_dwordx4 v[34:37], v[62:63], off
	s_nop 0
	global_load_dwordx4 v[38:41], v[38:39], off
	v_addc_co_u32_e32 v43, vcc, 0, v63, vcc
	v_add_co_u32_e32 v46, vcc, s96, v62
	v_readlane_b32 s6, v253, 7
	s_nop 0
	v_addc_co_u32_e32 v47, vcc, 0, v63, vcc
	v_add_co_u32_e32 v50, vcc, s2, v62
	s_mov_b32 s2, 0x28000
	s_nop 0
	v_addc_co_u32_e32 v51, vcc, 0, v63, vcc
	v_add_co_u32_e32 v54, vcc, s2, v62
	global_load_dwordx4 v[42:45], v[42:43], off
	s_nop 0
	global_load_dwordx4 v[46:49], v[46:47], off
	v_addc_co_u32_e32 v55, vcc, 0, v63, vcc
	global_load_dwordx4 v[50:53], v[50:51], off
	s_nop 0
	global_load_dwordx4 v[54:57], v[54:55], off
	s_mov_b32 s2, 0x30000
	v_add_co_u32_e32 v58, vcc, s2, v62
	s_mov_b32 s2, 0x38000
	s_nop 0
	v_addc_co_u32_e32 v59, vcc, 0, v63, vcc
	global_load_dwordx4 v[58:61], v[58:59], off
	v_add_co_u32_e32 v62, vcc, s2, v62
	v_readlane_b32 s7, v253, 8
	s_nop 0
	v_addc_co_u32_e32 v63, vcc, 0, v63, vcc
	global_load_dwordx4 v[62:65], v[62:63], off
	v_lshlrev_b32_e32 v0, 1, v33
	s_waitcnt vmcnt(7)
	ds_write2_b32 v18, v34, v35 offset1:1
	ds_write2_b32 v18, v36, v37 offset0:2 offset1:3
	s_waitcnt vmcnt(6)
	ds_write2_b32 v7, v38, v39 offset1:1
	ds_write2_b32 v20, v40, v41 offset1:1
	s_waitcnt vmcnt(5)
	ds_write2_b32 v21, v42, v43 offset1:1
	ds_write2_b32 v22, v44, v45 offset1:1
	s_waitcnt vmcnt(4)
	ds_write2_b32 v23, v46, v47 offset1:1
	ds_write2_b32 v24, v48, v49 offset1:1
	s_waitcnt vmcnt(3)
	ds_write2_b32 v25, v50, v51 offset1:1
	ds_write2_b32 v26, v52, v53 offset1:1
	s_waitcnt vmcnt(2)
	ds_write2_b32 v27, v54, v55 offset1:1
	ds_write2_b32 v28, v56, v57 offset1:1
	s_waitcnt vmcnt(1)
	ds_write2_b32 v29, v58, v59 offset1:1
	ds_write2_b32 v30, v60, v61 offset1:1
	s_waitcnt vmcnt(0)
	ds_write2_b32 v31, v62, v63 offset1:1
	ds_write2_b32 v32, v64, v65 offset1:1
	s_waitcnt lgkmcnt(0)
	ds_read2_b32 v[108:109], v15 offset1:33
	ds_read2_b32 v[110:111], v15 offset0:66 offset1:99
	ds_read2_b32 v[112:113], v15 offset0:132 offset1:165
	ds_read2_b32 v[114:115], v15 offset0:198 offset1:231
	ds_read2_b32 v[116:117], v15 offset0:8 offset1:41
	ds_read2_b32 v[118:119], v15 offset0:74 offset1:107
	ds_read2_b32 v[120:121], v15 offset0:140 offset1:173
	ds_read2_b32 v[122:123], v15 offset0:206 offset1:239
	ds_read2_b32 v[124:125], v15 offset0:16 offset1:49
	ds_read2_b32 v[126:127], v15 offset0:82 offset1:115
	ds_read2_b32 v[128:129], v15 offset0:148 offset1:181
	ds_read2_b32 v[130:131], v15 offset0:214 offset1:247
	s_waitcnt lgkmcnt(8)
	ds_read2_b32 v[132:133], v15 offset0:24 offset1:57
	ds_read2_b32 v[134:135], v15 offset0:90 offset1:123
	ds_read2_b32 v[136:137], v15 offset0:156 offset1:189
	ds_read2_b32 v[138:139], v15 offset0:222 offset1:255
	s_waitcnt lgkmcnt(0)
	v_lshlrev_b64 v[26:27], 22, v[66:67]
	v_lshl_add_u64 v[26:27], s[6:7], 0, v[26:27]
	v_cvt_pk_bf16_f32 v20, v108, v109
	v_mov_b32_e32 v7, v1
	v_or_b32_e32 v28, v68, v3
	v_lshl_add_u64 v[26:27], v[26:27], 0, v[0:1]
	v_cvt_pk_bf16_f32 v21, v110, v111
	v_lshlrev_b32_e32 v0, 12, v28
	v_lshl_add_u64 v[6:7], v[26:27], 0, v[6:7]
	v_cvt_pk_bf16_f32 v22, v112, v113
	v_cvt_pk_bf16_f32 v23, v114, v115
	v_lshl_add_u64 v[26:27], v[6:7], 0, v[0:1]
	global_store_dwordx4 v[26:27], v[20:23], off sc1
	v_or_b32_e32 v0, v68, v5
	v_lshlrev_b32_e32 v0, 12, v0
	v_cvt_pk_bf16_f32 v20, v116, v117
	v_cvt_pk_bf16_f32 v21, v118, v119
	v_cvt_pk_bf16_f32 v22, v120, v121
	v_cvt_pk_bf16_f32 v23, v122, v123
	v_lshl_add_u64 v[26:27], v[6:7], 0, v[0:1]
	global_store_dwordx4 v[26:27], v[20:23], off sc1
	v_or_b32_e32 v0, v68, v10
	v_lshlrev_b32_e32 v0, 12, v0
	v_cvt_pk_bf16_f32 v20, v124, v125
	v_cvt_pk_bf16_f32 v21, v126, v127
	v_cvt_pk_bf16_f32 v22, v128, v129
	v_cvt_pk_bf16_f32 v23, v130, v131
	v_lshl_add_u64 v[26:27], v[6:7], 0, v[0:1]
	v_or_b32_e32 v0, v68, v11
	global_store_dwordx4 v[26:27], v[20:23], off sc1
	v_lshlrev_b32_e32 v0, 12, v0
	v_lshl_add_u64 v[6:7], v[6:7], 0, v[0:1]
	v_cvt_pk_bf16_f32 v20, v132, v133
	v_cvt_pk_bf16_f32 v21, v134, v135
	v_cvt_pk_bf16_f32 v22, v136, v137
	v_cvt_pk_bf16_f32 v23, v138, v139
	global_store_dwordx4 v[6:7], v[20:23], off sc1
	s_waitcnt lgkmcnt(0)
.LBB0_163:
	s_andn2_saveexec_b64 s[20:21], s[20:21]
	s_cbranch_execz .LBB0_160
	v_ashrrev_i32_e32 v33, 31, v19
	v_lshrrev_b32_e32 v33, 21, v33
	v_add_u32_e32 v33, v19, v33
	v_ashrrev_i32_e32 v66, 11, v33
	v_and_b32_e32 v33, 0xfffff800, v33
	v_sub_u32_e32 v33, v19, v33
	v_ashrrev_i32_e32 v36, 31, v33
	v_lshrrev_b32_e32 v36, 25, v36
	v_add_u32_e32 v36, v33, v36
	v_ashrrev_i32_e32 v37, 7, v36
	v_and_b32_e32 v36, 0x7ffff80, v36
	v_ashrrev_i32_e32 v67, 31, v66
	v_readlane_b32 s52, v253, 15
	v_sub_u32_e32 v33, v33, v36
	v_lshlrev_b32_e32 v68, 6, v37
	v_lshlrev_b64 v[34:35], 24, v[66:67]
	v_readlane_b32 s62, v253, 25
	v_readlane_b32 s63, v253, 26
	v_lshlrev_b32_e32 v70, 5, v33
	v_or_b32_e32 v62, v68, v3
	v_lshl_add_u64 v[34:35], s[62:63], 0, v[34:35]
	v_ashrrev_i32_e32 v71, 31, v70
	v_or_b32_e32 v36, 8, v62
	v_or_b32_e32 v42, 16, v62
	v_or_b32_e32 v44, 24, v62
	v_or_b32_e32 v50, 32, v62
	v_or_b32_e32 v52, 40, v62
	v_lshl_add_u64 v[34:35], v[70:71], 2, v[34:35]
	v_ashrrev_i32_e32 v63, 31, v62
	v_ashrrev_i32_e32 v37, 31, v36
	v_ashrrev_i32_e32 v43, 31, v42
	v_ashrrev_i32_e32 v45, 31, v44
	v_ashrrev_i32_e32 v51, 31, v50
	v_ashrrev_i32_e32 v53, 31, v52
	v_lshl_add_u64 v[64:65], v[34:35], 0, v[0:1]
	v_lshlrev_b64 v[34:35], 14, v[62:63]
	v_lshlrev_b64 v[36:37], 14, v[36:37]
	v_lshlrev_b64 v[42:43], 14, v[42:43]
	v_lshlrev_b64 v[44:45], 14, v[44:45]
	v_lshlrev_b64 v[50:51], 14, v[50:51]
	v_lshlrev_b64 v[52:53], 14, v[52:53]
	v_lshl_add_u64 v[34:35], v[64:65], 0, v[34:35]
	v_lshl_add_u64 v[38:39], v[64:65], 0, v[36:37]
	v_lshl_add_u64 v[42:43], v[64:65], 0, v[42:43]
	v_lshl_add_u64 v[46:47], v[64:65], 0, v[44:45]
	v_lshl_add_u64 v[50:51], v[64:65], 0, v[50:51]
	v_lshl_add_u64 v[54:55], v[64:65], 0, v[52:53]
	global_load_dwordx4 v[34:37], v[34:35], off
	s_nop 0
	global_load_dwordx4 v[38:41], v[38:39], off
	s_nop 0
	global_load_dwordx4 v[42:45], v[42:43], off
	s_nop 0
	global_load_dwordx4 v[46:49], v[46:47], off
	s_nop 0
	global_load_dwordx4 v[50:53], v[50:51], off
	s_nop 0
	global_load_dwordx4 v[54:57], v[54:55], off
	v_or_b32_e32 v58, 48, v62
	v_ashrrev_i32_e32 v59, 31, v58
	v_lshlrev_b64 v[58:59], 14, v[58:59]
	v_or_b32_e32 v62, 56, v62
	v_lshl_add_u64 v[58:59], v[64:65], 0, v[58:59]
	v_ashrrev_i32_e32 v63, 31, v62
	global_load_dwordx4 v[58:61], v[58:59], off
	v_lshlrev_b64 v[62:63], 14, v[62:63]
	v_lshl_add_u64 v[62:63], v[64:65], 0, v[62:63]
	global_load_dwordx4 v[62:65], v[62:63], off
	v_ashrrev_i32_e32 v69, 31, v68
	v_readlane_b32 s61, v253, 24
	s_movk_i32 s61, 0xfff
	v_readlane_b32 s53, v253, 16
	v_readlane_b32 s54, v253, 17
	v_readlane_b32 s55, v253, 18
	v_readlane_b32 s56, v253, 19
	v_readlane_b32 s57, v253, 20
	v_readlane_b32 s58, v253, 21
	v_readlane_b32 s59, v253, 22
	v_readlane_b32 s60, v253, 23
	v_readlane_b32 s64, v253, 27
	v_readlane_b32 s65, v253, 28
	v_readlane_b32 s66, v253, 29
	v_readlane_b32 s67, v253, 30
	s_waitcnt vmcnt(7)
	ds_write2_b32 v18, v34, v35 offset1:1
	ds_write2_b32 v18, v36, v37 offset0:2 offset1:3
	s_waitcnt vmcnt(6)
	ds_write2_b32 v7, v38, v39 offset1:1
	ds_write2_b32 v20, v40, v41 offset1:1
	s_waitcnt vmcnt(5)
	ds_write2_b32 v21, v42, v43 offset1:1
	ds_write2_b32 v22, v44, v45 offset1:1
	s_waitcnt vmcnt(4)
	ds_write2_b32 v23, v46, v47 offset1:1
	ds_write2_b32 v24, v48, v49 offset1:1
	s_waitcnt vmcnt(3)
	ds_write2_b32 v25, v50, v51 offset1:1
	ds_write2_b32 v26, v52, v53 offset1:1
	s_waitcnt vmcnt(2)
	ds_write2_b32 v27, v54, v55 offset1:1
	ds_write2_b32 v28, v56, v57 offset1:1
	s_waitcnt vmcnt(1)
	ds_write2_b32 v29, v58, v59 offset1:1
	ds_write2_b32 v30, v60, v61 offset1:1
	s_waitcnt vmcnt(0)
	ds_write2_b32 v31, v62, v63 offset1:1
	ds_write2_b32 v32, v64, v65 offset1:1
	s_waitcnt lgkmcnt(0)
	ds_read2_b32 v[108:109], v15 offset1:33
	ds_read2_b32 v[110:111], v15 offset0:66 offset1:99
	ds_read2_b32 v[112:113], v15 offset0:132 offset1:165
	ds_read2_b32 v[114:115], v15 offset0:198 offset1:231
	ds_read2_b32 v[116:117], v15 offset0:8 offset1:41
	ds_read2_b32 v[118:119], v15 offset0:74 offset1:107
	ds_read2_b32 v[120:121], v15 offset0:140 offset1:173
	ds_read2_b32 v[122:123], v15 offset0:206 offset1:239
	ds_read2_b32 v[124:125], v15 offset0:16 offset1:49
	ds_read2_b32 v[126:127], v15 offset0:82 offset1:115
	ds_read2_b32 v[128:129], v15 offset0:148 offset1:181
	ds_read2_b32 v[130:131], v15 offset0:214 offset1:247
	s_waitcnt lgkmcnt(8)
	ds_read2_b32 v[132:133], v15 offset0:24 offset1:57
	ds_read2_b32 v[134:135], v15 offset0:90 offset1:123
	ds_read2_b32 v[136:137], v15 offset0:156 offset1:189
	ds_read2_b32 v[138:139], v15 offset0:222 offset1:255
	s_waitcnt lgkmcnt(0)
	v_cvt_pk_bf16_f32 v20, v108, v109
	v_lshlrev_b64 v[24:25], 23, v[66:67]
	v_cvt_pk_bf16_f32 v21, v110, v111
	v_lshl_add_u64 v[24:25], s[90:91], 0, v[24:25]
	v_or_b32_e32 v28, v70, v3
	v_mov_b32_e32 v7, v1
	v_cvt_pk_bf16_f32 v22, v112, v113
	v_lshl_add_u64 v[24:25], v[68:69], 1, v[24:25]
	v_ashrrev_i32_e32 v29, 31, v28
	v_lshl_add_u64 v[6:7], v[24:25], 0, v[6:7]
	v_cvt_pk_bf16_f32 v23, v114, v115
	v_lshlrev_b64 v[26:27], 11, v[28:29]
	v_lshl_add_u64 v[26:27], v[6:7], 0, v[26:27]
	global_store_dwordx4 v[26:27], v[20:23], off sc1
	v_or_b32_e32 v26, v70, v5
	v_ashrrev_i32_e32 v27, 31, v26
	v_cvt_pk_bf16_f32 v20, v116, v117
	v_lshlrev_b64 v[26:27], 11, v[26:27]
	v_cvt_pk_bf16_f32 v21, v118, v119
	v_lshl_add_u64 v[26:27], v[6:7], 0, v[26:27]
	v_cvt_pk_bf16_f32 v22, v120, v121
	v_cvt_pk_bf16_f32 v23, v122, v123
	global_store_dwordx4 v[26:27], v[20:23], off sc1
	v_or_b32_e32 v26, v70, v10
	v_ashrrev_i32_e32 v27, 31, v26
	v_cvt_pk_bf16_f32 v20, v124, v125
	v_lshlrev_b64 v[26:27], 11, v[26:27]
	v_cvt_pk_bf16_f32 v21, v126, v127
	v_lshl_add_u64 v[26:27], v[6:7], 0, v[26:27]
	v_cvt_pk_bf16_f32 v22, v128, v129
	v_cvt_pk_bf16_f32 v23, v130, v131
	global_store_dwordx4 v[26:27], v[20:23], off sc1
	v_or_b32_e32 v26, v70, v11
	v_ashrrev_i32_e32 v27, 31, v26
	v_cvt_pk_bf16_f32 v20, v132, v133
	v_lshlrev_b64 v[26:27], 11, v[26:27]
	v_cvt_pk_bf16_f32 v21, v134, v135
	v_lshl_add_u64 v[6:7], v[6:7], 0, v[26:27]
	v_cvt_pk_bf16_f32 v22, v136, v137
	v_cvt_pk_bf16_f32 v23, v138, v139
	global_store_dwordx4 v[6:7], v[20:23], off sc1
	s_waitcnt lgkmcnt(0)
	s_branch .LBB0_160

.LBB0_168:
	v_add_u32_e32 v0, 0x100, v14
	s_movk_i32 s2, 0xff
	v_cmp_lt_i32_e32 vcc, s2, v0
	v_lshlrev_b32_e32 v8, 2, v2
	v_add_u32_e32 v18, 0x420, v12
	v_add_u32_e32 v19, 0x428, v12
	v_add_u32_e32 v20, 0x840, v12
	v_add_u32_e32 v21, 0x848, v12
	v_add_u32_e32 v22, 0xc60, v12
	v_add_u32_e32 v23, 0xc68, v12
	v_add_u32_e32 v24, 0x1080, v12
	v_add_u32_e32 v25, 0x1088, v12
	v_add_u32_e32 v26, 0x14a0, v12
	v_add_u32_e32 v27, 0x14a8, v12
	v_add_u32_e32 v28, 0x18c0, v12
	v_add_u32_e32 v29, 0x18c8, v12
	v_add_u32_e32 v30, 0x1ce0, v12
	v_add_u32_e32 v7, 0x1ce8, v12
	v_lshlrev_b32_e32 v6, 1, v4
	s_and_saveexec_b64 s[6:7], vcc
	s_xor_b64 s[20:21], exec, s[6:7]
	s_cbranch_execz .LBB0_170
	v_lshrrev_b32_e32 v0, 5, v14
	v_lshlrev_b64 v[32:33], 18, v[0:1]
	v_and_b32_e32 v66, 0xe0, v16
	v_lshl_add_u64 v[32:33], s[78:79], 0, v[32:33]
	v_lshlrev_b64 v[64:65], 17, v[0:1]
	v_and_b32_e32 v31, 0xc0, v15
	v_lshlrev_b32_e32 v0, 2, v66
	v_or_b32_e32 v34, v31, v3
	v_lshl_add_u64 v[32:33], v[32:33], 0, v[0:1]
	v_mov_b32_e32 v9, v1
	v_lshl_add_u64 v[8:9], v[32:33], 0, v[8:9]
	v_lshlrev_b32_e32 v0, 10, v34
	v_lshl_add_u64 v[8:9], v[8:9], 0, v[0:1]
	s_movk_i32 s2, 0x2000
	v_add_co_u32_e32 v36, vcc, s2, v8
	s_movk_i32 s2, 0x4000
	s_nop 0
	v_addc_co_u32_e32 v37, vcc, 0, v9, vcc
	v_add_co_u32_e32 v40, vcc, s2, v8
	s_mov_b32 s2, 0xa000
	s_nop 0
	v_addc_co_u32_e32 v41, vcc, 0, v9, vcc
	v_add_co_u32_e32 v44, vcc, s5, v8
	global_load_dwordx4 v[32:35], v[8:9], off
	s_nop 0
	global_load_dwordx4 v[36:39], v[36:37], off
	v_addc_co_u32_e32 v45, vcc, 0, v9, vcc
	v_add_co_u32_e32 v48, vcc, s97, v8
	global_load_dwordx4 v[40:43], v[40:41], off
	s_nop 0
	global_load_dwordx4 v[44:47], v[44:45], off
	v_addc_co_u32_e32 v49, vcc, 0, v9, vcc
	v_add_co_u32_e32 v52, vcc, s2, v8
	s_mov_b32 s2, 0xe000
	s_nop 0
	v_addc_co_u32_e32 v53, vcc, 0, v9, vcc
	global_load_dwordx4 v[48:51], v[48:49], off
	s_nop 0
	global_load_dwordx4 v[52:55], v[52:53], off
	v_add_co_u32_e32 v56, vcc, s50, v8
	v_readlane_b32 s6, v253, 11
	s_nop 0
	v_addc_co_u32_e32 v57, vcc, 0, v9, vcc
	global_load_dwordx4 v[56:59], v[56:57], off
	v_add_co_u32_e32 v8, vcc, s2, v8
	v_readlane_b32 s7, v253, 12
	s_nop 0
	v_addc_co_u32_e32 v9, vcc, 0, v9, vcc
	global_load_dwordx4 v[60:63], v[8:9], off
	v_lshlrev_b32_e32 v0, 1, v31
	s_waitcnt vmcnt(7)
	ds_write2_b32 v12, v32, v33 offset1:1
	ds_write2_b32 v12, v34, v35 offset0:2 offset1:3
	s_waitcnt vmcnt(6)
	ds_write2_b32 v18, v36, v37 offset1:1
	ds_write2_b32 v19, v38, v39 offset1:1
	s_waitcnt vmcnt(5)
	ds_write2_b32 v20, v40, v41 offset1:1
	ds_write2_b32 v21, v42, v43 offset1:1
	s_waitcnt vmcnt(4)
	ds_write2_b32 v22, v44, v45 offset1:1
	ds_write2_b32 v23, v46, v47 offset1:1
	s_waitcnt vmcnt(3)
	ds_write2_b32 v24, v48, v49 offset1:1
	ds_write2_b32 v25, v50, v51 offset1:1
	s_waitcnt vmcnt(2)
	ds_write2_b32 v26, v52, v53 offset1:1
	ds_write2_b32 v27, v54, v55 offset1:1
	s_waitcnt vmcnt(1)
	ds_write2_b32 v28, v56, v57 offset1:1
	ds_write2_b32 v29, v58, v59 offset1:1
	s_waitcnt vmcnt(0)
	ds_write2_b32 v30, v60, v61 offset1:1
	ds_write2_b32 v7, v62, v63 offset1:1
	s_waitcnt lgkmcnt(0)
	ds_read2_b32 v[108:109], v13 offset1:33
	ds_read2_b32 v[110:111], v13 offset0:66 offset1:99
	ds_read2_b32 v[112:113], v13 offset0:132 offset1:165
	ds_read2_b32 v[114:115], v13 offset0:198 offset1:231
	ds_read2_b32 v[116:117], v13 offset0:8 offset1:41
	ds_read2_b32 v[118:119], v13 offset0:74 offset1:107
	ds_read2_b32 v[120:121], v13 offset0:140 offset1:173
	ds_read2_b32 v[122:123], v13 offset0:206 offset1:239
	ds_read2_b32 v[124:125], v13 offset0:16 offset1:49
	ds_read2_b32 v[126:127], v13 offset0:82 offset1:115
	ds_read2_b32 v[128:129], v13 offset0:148 offset1:181
	ds_read2_b32 v[130:131], v13 offset0:214 offset1:247
	s_waitcnt lgkmcnt(8)
	ds_read2_b32 v[132:133], v13 offset0:24 offset1:57
	ds_read2_b32 v[134:135], v13 offset0:90 offset1:123
	ds_read2_b32 v[136:137], v13 offset0:156 offset1:189
	ds_read2_b32 v[138:139], v13 offset0:222 offset1:255
	s_waitcnt lgkmcnt(0)
	v_cvt_pk_bf16_f32 v18, v108, v109
	v_lshl_add_u64 v[22:23], s[6:7], 0, v[64:65]
	v_cvt_pk_bf16_f32 v19, v110, v111
	v_mov_b32_e32 v7, v1
	v_or_b32_e32 v24, v66, v3
	v_lshl_add_u64 v[22:23], v[22:23], 0, v[0:1]
	v_cvt_pk_bf16_f32 v20, v112, v113
	v_lshlrev_b32_e32 v0, 9, v24
	v_lshl_add_u64 v[22:23], v[22:23], 0, v[6:7]
	v_cvt_pk_bf16_f32 v21, v114, v115
	v_lshl_add_u64 v[6:7], v[22:23], 0, v[0:1]
	global_store_dwordx4 v[6:7], v[18:21], off sc1
	v_cvt_pk_bf16_f32 v6, v116, v117
	v_or_b32_e32 v0, v66, v5
	v_cvt_pk_bf16_f32 v7, v118, v119
	v_lshlrev_b32_e32 v0, 9, v0
	v_cvt_pk_bf16_f32 v8, v120, v121
	v_cvt_pk_bf16_f32 v9, v122, v123
	v_lshl_add_u64 v[20:21], v[22:23], 0, v[0:1]
	global_store_dwordx4 v[20:21], v[6:9], off sc1
	v_or_b32_e32 v0, v66, v10
	v_lshlrev_b32_e32 v0, 9, v0
	v_cvt_pk_bf16_f32 v6, v124, v125
	v_cvt_pk_bf16_f32 v7, v126, v127
	v_cvt_pk_bf16_f32 v8, v128, v129
	v_cvt_pk_bf16_f32 v9, v130, v131
	v_lshl_add_u64 v[20:21], v[22:23], 0, v[0:1]
	global_store_dwordx4 v[20:21], v[6:9], off sc1
	v_or_b32_e32 v0, v66, v11
	v_lshlrev_b32_e32 v0, 9, v0
	v_cvt_pk_bf16_f32 v6, v132, v133
	v_cvt_pk_bf16_f32 v7, v134, v135
	v_cvt_pk_bf16_f32 v8, v136, v137
	v_cvt_pk_bf16_f32 v9, v138, v139
	v_lshl_add_u64 v[18:19], v[22:23], 0, v[0:1]
	global_store_dwordx4 v[18:19], v[6:9], off sc1
	s_waitcnt lgkmcnt(0)
.LBB0_170:
	s_andn2_saveexec_b64 s[20:21], s[20:21]
	s_cbranch_execz .LBB0_167
	v_bfe_u32 v31, v0, 3, 1
	v_ashrrev_i32_e32 v32, 4, v0
	v_and_b32_e32 v66, 3, v0
	v_mov_b32_e32 v0, s73
	v_mov_b32_e32 v9, s69
	v_cmp_eq_u32_e32 vcc, 0, v31
	v_ashrrev_i32_e32 v33, 31, v32
	v_lshlrev_b64 v[64:65], 16, v[32:33]
	v_cndmask_b32_e32 v35, v0, v9, vcc
	v_mov_b32_e32 v0, s72
	v_mov_b32_e32 v9, s68
	v_cndmask_b32_e32 v34, v0, v9, vcc
	v_lshl_add_u64 v[32:33], v[34:35], 0, v[64:65]
	v_and_b32_e32 v67, 64, v17
	v_lshlrev_b32_e32 v0, 7, v66
	v_or_b32_e32 v34, v67, v3
	v_lshl_add_u64 v[32:33], v[32:33], 0, v[0:1]
	v_mov_b32_e32 v9, v1
	v_lshl_add_u64 v[8:9], v[32:33], 0, v[8:9]
	v_lshlrev_b32_e32 v0, 9, v34
	v_lshl_add_u64 v[8:9], v[8:9], 0, v[0:1]
	s_movk_i32 s2, 0x2000
	v_add_co_u32_e32 v40, vcc, s2, v8
	s_movk_i32 s2, 0x4000
	s_nop 0
	v_addc_co_u32_e32 v41, vcc, 0, v9, vcc
	v_add_co_u32_e32 v48, vcc, s2, v8
	s_movk_i32 s2, 0x7000
	s_nop 0
	v_addc_co_u32_e32 v49, vcc, 0, v9, vcc
	v_add_co_u32_e32 v56, vcc, s5, v8
	global_load_dwordx4 v[32:35], v[8:9], off
	s_nop 0
	v_addc_co_u32_e32 v57, vcc, 0, v9, vcc
	v_add_co_u32_e32 v8, vcc, s2, v8
	global_load_dwordx4 v[36:39], v[40:41], off offset:-4096
	s_nop 0
	global_load_dwordx4 v[40:43], v[40:41], off
	v_addc_co_u32_e32 v9, vcc, 0, v9, vcc
	global_load_dwordx4 v[44:47], v[48:49], off offset:-4096
	s_nop 0
	global_load_dwordx4 v[48:51], v[48:49], off
	s_nop 0
	global_load_dwordx4 v[52:55], v[56:57], off offset:-4096
	s_nop 0
	global_load_dwordx4 v[56:59], v[56:57], off
	v_readlane_b32 s6, v253, 9
	global_load_dwordx4 v[60:63], v[8:9], off
	v_readlane_b32 s7, v253, 10
	s_waitcnt vmcnt(7)
	v_mul_f32_e32 v0, 0xbfb8aa3b, v32
	v_mul_f32_e32 v8, 0xbfb8aa3b, v33
	v_mul_f32_e32 v9, 0xbfb8aa3b, v34
	v_mul_f32_e32 v32, 0xbfb8aa3b, v35
	ds_write2_b32 v12, v0, v8 offset1:1
	ds_write2_b32 v12, v9, v32 offset0:2 offset1:3
	s_waitcnt vmcnt(6)
	v_mul_f32_e32 v0, 0xbfb8aa3b, v36
	v_mul_f32_e32 v8, 0xbfb8aa3b, v37
	v_mul_f32_e32 v9, 0xbfb8aa3b, v38
	v_mul_f32_e32 v32, 0xbfb8aa3b, v39
	s_waitcnt vmcnt(5)
	v_mul_f32_e32 v33, 0xbfb8aa3b, v40
	v_mul_f32_e32 v34, 0xbfb8aa3b, v41
	v_mul_f32_e32 v35, 0xbfb8aa3b, v42
	v_mul_f32_e32 v36, 0xbfb8aa3b, v43
	s_waitcnt vmcnt(4)
	v_mul_f32_e32 v37, 0xbfb8aa3b, v44
	v_mul_f32_e32 v38, 0xbfb8aa3b, v45
	v_mul_f32_e32 v39, 0xbfb8aa3b, v46
	v_mul_f32_e32 v40, 0xbfb8aa3b, v47
	s_waitcnt vmcnt(3)
	v_mul_f32_e32 v41, 0xbfb8aa3b, v48
	v_mul_f32_e32 v42, 0xbfb8aa3b, v49
	v_mul_f32_e32 v43, 0xbfb8aa3b, v50
	v_mul_f32_e32 v44, 0xbfb8aa3b, v51
	s_waitcnt vmcnt(2)
	v_mul_f32_e32 v45, 0xbfb8aa3b, v52
	v_mul_f32_e32 v46, 0xbfb8aa3b, v53
	v_mul_f32_e32 v47, 0xbfb8aa3b, v54
	v_mul_f32_e32 v48, 0xbfb8aa3b, v55
	s_waitcnt vmcnt(1)
	v_mul_f32_e32 v49, 0xbfb8aa3b, v56
	v_mul_f32_e32 v50, 0xbfb8aa3b, v57
	v_mul_f32_e32 v51, 0xbfb8aa3b, v58
	v_mul_f32_e32 v52, 0xbfb8aa3b, v59
	s_waitcnt vmcnt(0)
	v_mul_f32_e32 v53, 0xbfb8aa3b, v60
	v_mul_f32_e32 v54, 0xbfb8aa3b, v61
	ds_write2_b32 v18, v0, v8 offset1:1
	ds_write2_b32 v19, v9, v32 offset1:1
	ds_write2_b32 v20, v33, v34 offset1:1
	ds_write2_b32 v21, v35, v36 offset1:1
	ds_write2_b32 v22, v37, v38 offset1:1
	ds_write2_b32 v23, v39, v40 offset1:1
	ds_write2_b32 v24, v41, v42 offset1:1
	ds_write2_b32 v25, v43, v44 offset1:1
	ds_write2_b32 v26, v45, v46 offset1:1
	ds_write2_b32 v27, v47, v48 offset1:1
	ds_write2_b32 v28, v49, v50 offset1:1
	ds_write2_b32 v29, v51, v52 offset1:1
	ds_write2_b32 v30, v53, v54 offset1:1
	v_mul_f32_e32 v0, 0xbfb8aa3b, v62
	v_mul_f32_e32 v8, 0xbfb8aa3b, v63
	ds_write2_b32 v7, v0, v8 offset1:1
	s_waitcnt lgkmcnt(0)
	ds_read2_b32 v[108:109], v13 offset1:33
	ds_read2_b32 v[110:111], v13 offset0:66 offset1:99
	ds_read2_b32 v[112:113], v13 offset0:132 offset1:165
	ds_read2_b32 v[114:115], v13 offset0:198 offset1:231
	ds_read2_b32 v[116:117], v13 offset0:8 offset1:41
	ds_read2_b32 v[118:119], v13 offset0:74 offset1:107
	ds_read2_b32 v[120:121], v13 offset0:140 offset1:173
	ds_read2_b32 v[122:123], v13 offset0:206 offset1:239
	ds_read2_b32 v[124:125], v13 offset0:16 offset1:49
	ds_read2_b32 v[126:127], v13 offset0:82 offset1:115
	ds_read2_b32 v[128:129], v13 offset0:148 offset1:181
	ds_read2_b32 v[130:131], v13 offset0:214 offset1:247
	s_waitcnt lgkmcnt(8)
	ds_read2_b32 v[132:133], v13 offset0:24 offset1:57
	ds_read2_b32 v[134:135], v13 offset0:90 offset1:123
	ds_read2_b32 v[136:137], v13 offset0:156 offset1:189
	ds_read2_b32 v[138:139], v13 offset0:222 offset1:255
	s_waitcnt lgkmcnt(0)
	v_lshlrev_b32_e32 v0, 6, v66
	v_cvt_pk_bf16_f32 v18, v108, v109
	v_lshl_or_b32 v24, v31, 5, v0
	v_lshl_add_u64 v[22:23], s[6:7], 0, v[64:65]
	v_lshlrev_b32_e32 v0, 1, v67
	v_cvt_pk_bf16_f32 v19, v110, v111
	v_mov_b32_e32 v7, v1
	v_or_b32_e32 v25, v24, v3
	v_lshl_add_u64 v[22:23], v[22:23], 0, v[0:1]
	v_cvt_pk_bf16_f32 v20, v112, v113
	v_lshlrev_b32_e32 v0, 8, v25
	v_lshl_add_u64 v[22:23], v[22:23], 0, v[6:7]
	v_cvt_pk_bf16_f32 v21, v114, v115
	v_lshl_add_u64 v[6:7], v[22:23], 0, v[0:1]
	global_store_dwordx4 v[6:7], v[18:21], off sc1
	v_cvt_pk_bf16_f32 v6, v116, v117
	v_or_b32_e32 v0, v24, v5
	v_cvt_pk_bf16_f32 v7, v118, v119
	v_lshlrev_b32_e32 v0, 8, v0
	v_cvt_pk_bf16_f32 v8, v120, v121
	v_cvt_pk_bf16_f32 v9, v122, v123
	v_lshl_add_u64 v[20:21], v[22:23], 0, v[0:1]
	global_store_dwordx4 v[20:21], v[6:9], off sc1
	v_or_b32_e32 v0, v24, v10
	v_lshlrev_b32_e32 v0, 8, v0
	v_cvt_pk_bf16_f32 v6, v124, v125
	v_cvt_pk_bf16_f32 v7, v126, v127
	v_cvt_pk_bf16_f32 v8, v128, v129
	v_cvt_pk_bf16_f32 v9, v130, v131
	v_lshl_add_u64 v[20:21], v[22:23], 0, v[0:1]
	global_store_dwordx4 v[20:21], v[6:9], off sc1
	v_or_b32_e32 v0, v24, v11
	v_lshlrev_b32_e32 v0, 8, v0
	v_cvt_pk_bf16_f32 v6, v132, v133
	v_cvt_pk_bf16_f32 v7, v134, v135
	v_cvt_pk_bf16_f32 v8, v136, v137
	v_cvt_pk_bf16_f32 v9, v138, v139
	v_lshl_add_u64 v[18:19], v[22:23], 0, v[0:1]
	global_store_dwordx4 v[18:19], v[6:9], off sc1
	s_waitcnt lgkmcnt(0)
	s_branch .LBB0_167
